# rope-table loads batched, V-transpose path bias hoisted, mixers2 queue: half of the workgroups start with a windowed-attention item so recurrence (latency-bound) and attention (issue-bound) items over
# speedup vs baseline: 1.0715x; 1.0212x over previous
; DI unsigned pk2(float a, float b) { hwf32x2 f = {a, b}; hwbf16x2 r = __builtin_convertvector(f, hwbf16x2); return __builtin_bit_cast(unsigned, r); }
;   DI void operator()(int mt, int nt, int wm, int wn, int r, int h, f32x16 (&acc)[WM][2]) const {
;     ...
;         for (int j = 0; j < 8; ++j) {
;           const int id = tid + 256 * j;
;           const int c = id & 127, rg = id >> 7;
;           const int lr0 = rg * 8;
;           const int row = mt * (WM * 64) + (lr0 >> 6) * (WM * 32) + ps * 64 + (lr0 & 63);
;           const int b = row / NTOK, t = row % NTOK;
;           const int col = nt * 128 + c;
;           const float bb = bias[col];
;           float x[8];
; #pragma unroll
;           for (int k = 0; k < 8; ++k) x[k] = T[(lr0 + k) * LD + c] + bb;
;           bf16_t* vt = (nt == 17) ? VTC + ((size_t)b * 128 + (col - C_V)) * NTOK : VTA + ((size_t)b * 256 + (col - A_V)) * NTOK;
;           *(uint4*)(vt + t) = make_uint4(pk2(x[0], x[1]), pk2(x[2], x[3]), pk2(x[4], x[5]), pk2(x[6], x[7]));
;         }
.LBB0_161:
	s_add_u32 s0, s68, s0
	s_waitcnt lgkmcnt(0)
	v_mov_b32_e32 v0, v244
	v_pk_add_f32 v[2:3], v[0:1], v[2:3] op_sel_hi:[0,1]
	v_pk_add_f32 v[4:5], v[0:1], v[4:5] op_sel_hi:[0,1]
	v_pk_add_f32 v[6:7], v[0:1], v[6:7] op_sel_hi:[0,1]
	v_pk_add_f32 v[8:9], v[0:1], v[8:9] op_sel_hi:[0,1]
	v_mul_i32_i24_e32 v0, 0x900, v12
	s_addc_u32 s1, s69, s1
	v_sub_u32_e32 v12, v1, v0
	v_mov_b64_e32 v[0:1], s[0:1]
	v_mad_u64_u32 v[14:15], s[0:1], v10, s67, v[0:1]
	v_mov_b32_e32 v0, v15
	v_mad_u64_u32 v[0:1], s[0:1], v11, s67, v[0:1]
	v_mov_b32_e32 v15, v0
	v_ashrrev_i32_e32 v13, 31, v12
	v_cvt_pk_bf16_f32 v0, v2, v3
	v_cvt_pk_bf16_f32 v1, v4, v5
	v_cvt_pk_bf16_f32 v2, v6, v7
	v_cvt_pk_bf16_f32 v3, v8, v9
	v_lshl_add_u64 v[4:5], v[12:13], 1, v[14:15]
	global_store_dwordx4 v[4:5], v[0:3], off

; DI unsigned pk2(float a, float b) { hwf32x2 f = {a, b}; hwbf16x2 r = __builtin_convertvector(f, hwbf16x2); return __builtin_bit_cast(unsigned, r); }
;   DI void operator()(int mt, int nt, int wm, int wn, int r, int h, f32x16 (&acc)[WM][2]) const {
;     ...
;           if (ropemode != 0) {
;             const int pc = (ropemode == 1) ? (cc ^ 1) : (cc ^ 2);
;             const float4 p0 = *(const float4*)(T + lr * LD + pc * 8), p1 = *(const float4*)(T + lr * LD + pc * 8 + 4);
;             const float4 c0 = *(const float4*)(bias + nt * 128 + pc * 8), c1 = *(const float4*)(bias + nt * 128 + pc * 8 + 4);
;             const float pr[8] = {p0.x + c0.x, p0.y + c0.y, p0.z + c0.z, p0.w + c0.w, p1.x + c1.x, p1.y + c1.y, p1.z + c1.z, p1.w + c1.w};
;             const int tok = t - NCTX;
;             const int q = (ropemode == 1) ? (cc & 3) : ((cc & 7) >> 1);
;             const int pos = (q < 2) ? (tok >> 6) : (tok & 63);
;             const float2* tab = (ropemode == 1) ? (T32 + pos * 8) : (T64 + pos * 16 + (cc & 1) * 8);
;             const float sgn = (q & 1) ? 1.f : -1.f;
; #pragma unroll
;             for (int k = 0; k < 8; ++k) { const float2 cs = tab[k]; v[k] = v[k] * cs.x + sgn * pr[k] * cs.y; }
;           }
;           *(uint4*)(P + (size_t)row * PW + col0) = make_uint4(pk2(v[0], v[1]), pk2(v[2], v[3]), pk2(v[4], v[5]), pk2(v[6], v[7]));
.LBB0_177:
	global_load_dwordx4 v[228:231], v[92:93], off
	global_load_dwordx4 v[232:235], v[92:93], off offset:16
	global_load_dwordx4 v[236:239], v[92:93], off offset:32
	global_load_dwordx4 v[240:243], v[92:93], off offset:48
	s_waitcnt vmcnt(0) lgkmcnt(1)
	v_add_f32_e32 v80, v84, v80
	v_add_f32_e32 v81, v85, v81
	v_add_f32_e32 v84, v86, v82
	v_add_f32_e32 v85, v87, v83
	s_waitcnt lgkmcnt(0)
	v_add_f32_e32 v86, v76, v72
	v_add_f32_e32 v87, v77, v73
	v_add_f32_e32 v91, v78, v74
	v_add_f32_e32 v95, v79, v75
	v_mov_b32_e32 v72, v228
	v_mov_b32_e32 v73, v229
	v_mov_b32_e32 v74, v230
	v_mov_b32_e32 v75, v231
	v_mov_b32_e32 v79, v69
	v_cndmask_b32_e64 v78, v80, -v80, s[0:1]
	v_cndmask_b32_e64 v84, v84, -v84, s[0:1]
	v_cndmask_b32_e64 v86, v86, -v86, s[0:1]
	s_waitcnt vmcnt(0) lgkmcnt(0)
	v_mov_b32_e32 v76, v73
	v_cndmask_b32_e64 v73, v81, -v81, s[0:1]
	v_mov_b32_e32 v69, v73
	v_mov_b32_e32 v73, v75
	v_mov_b32_e32 v77, v74
	v_pk_mul_f32 v[80:81], v[68:69], v[72:73]
	v_mov_b32_e32 v72, v232
	v_mov_b32_e32 v73, v233
	v_mov_b32_e32 v74, v234
	v_mov_b32_e32 v75, v235
	v_cndmask_b32_e64 v68, v85, -v85, s[0:1]
	v_mov_b32_e32 v85, v71
	v_mov_b32_e32 v71, v68
	s_waitcnt vmcnt(0) lgkmcnt(0)
	v_mov_b32_e32 v82, v73
	v_mov_b32_e32 v73, v75
	v_pk_mul_f32 v[72:73], v[70:71], v[72:73]
	v_mov_b32_e32 v68, v236
	v_mov_b32_e32 v69, v237
	v_mov_b32_e32 v70, v238
	v_mov_b32_e32 v71, v239
	v_mov_b32_e32 v83, v74
	s_waitcnt vmcnt(0) lgkmcnt(0)
	v_mov_b32_e32 v74, v69
	v_cndmask_b32_e64 v69, v87, -v87, s[0:1]
	v_mov_b32_e32 v87, v65
	v_mov_b32_e32 v65, v69
	v_mov_b32_e32 v69, v71
	v_mov_b32_e32 v75, v70
	v_pk_mul_f32 v[64:65], v[64:65], v[68:69]
	v_mov_b32_e32 v68, v240
	v_mov_b32_e32 v69, v241
	v_mov_b32_e32 v70, v242
	v_mov_b32_e32 v71, v243
	v_pk_fma_f32 v[64:65], v[86:87], v[74:75], v[64:65]
	s_waitcnt vmcnt(0) lgkmcnt(0)
	v_mul_f32_e32 v66, v66, v68
	v_cndmask_b32_e64 v68, v91, -v91, s[0:1]
	v_mul_f32_e32 v92, v68, v69
	v_cndmask_b32_e64 v69, v95, -v95, s[0:1]
	v_mov_b32_e32 v68, v67
	v_pk_mul_f32 v[68:69], v[68:69], v[70:71]
	v_pk_fma_f32 v[70:71], v[84:85], v[82:83], v[72:73]
	v_mov_b32_e32 v67, v68
	v_mov_b32_e32 v93, v69
	v_pk_fma_f32 v[68:69], v[78:79], v[76:77], v[80:81]
	v_pk_add_f32 v[66:67], v[66:67], v[92:93]

; DI unsigned pk2(float a, float b) { hwf32x2 f = {a, b}; hwbf16x2 r = __builtin_convertvector(f, hwbf16x2); return __builtin_bit_cast(unsigned, r); }
;   DI void operator()(int mt, int nt, int wm, int wn, int r, int h, f32x16 (&acc)[WM][2]) const {
;     ...
;           if (ropemode != 0) {
;             const int pc = (ropemode == 1) ? (cc ^ 1) : (cc ^ 2);
;             const float4 p0 = *(const float4*)(T + lr * LD + pc * 8), p1 = *(const float4*)(T + lr * LD + pc * 8 + 4);
;             const float4 c0 = *(const float4*)(bias + nt * 128 + pc * 8), c1 = *(const float4*)(bias + nt * 128 + pc * 8 + 4);
;             const float pr[8] = {p0.x + c0.x, p0.y + c0.y, p0.z + c0.z, p0.w + c0.w, p1.x + c1.x, p1.y + c1.y, p1.z + c1.z, p1.w + c1.w};
;             const int tok = t - NCTX;
;             const int q = (ropemode == 1) ? (cc & 3) : ((cc & 7) >> 1);
;             const int pos = (q < 2) ? (tok >> 6) : (tok & 63);
;             const float2* tab = (ropemode == 1) ? (T32 + pos * 8) : (T64 + pos * 16 + (cc & 1) * 8);
;             const float sgn = (q & 1) ? 1.f : -1.f;
; #pragma unroll
;             for (int k = 0; k < 8; ++k) { const float2 cs = tab[k]; v[k] = v[k] * cs.x + sgn * pr[k] * cs.y; }
;           }
;           *(uint4*)(P + (size_t)row * PW + col0) = make_uint4(pk2(v[0], v[1]), pk2(v[2], v[3]), pk2(v[4], v[5]), pk2(v[6], v[7]));
.LBB0_186:
	global_load_dwordx4 v[228:231], v[92:93], off
	global_load_dwordx4 v[232:235], v[92:93], off offset:16
	global_load_dwordx4 v[236:239], v[92:93], off offset:32
	global_load_dwordx4 v[240:243], v[92:93], off offset:48
	s_waitcnt vmcnt(0) lgkmcnt(1)
	v_add_f32_e32 v80, v84, v80
	v_add_f32_e32 v81, v85, v81
	v_add_f32_e32 v84, v86, v82
	v_add_f32_e32 v85, v87, v83
	s_waitcnt lgkmcnt(0)
	v_add_f32_e32 v86, v76, v72
	v_add_f32_e32 v87, v77, v73
	v_add_f32_e32 v91, v78, v74
	v_add_f32_e32 v96, v79, v75
	v_mov_b32_e32 v72, v228
	v_mov_b32_e32 v73, v229
	v_mov_b32_e32 v74, v230
	v_mov_b32_e32 v75, v231
	v_mov_b32_e32 v79, v69
	v_cndmask_b32_e64 v78, v80, -v80, s[0:1]
	v_cndmask_b32_e64 v84, v84, -v84, s[0:1]
	v_cndmask_b32_e64 v86, v86, -v86, s[0:1]
	s_waitcnt vmcnt(0) lgkmcnt(0)
	v_mov_b32_e32 v76, v73
	v_cndmask_b32_e64 v73, v81, -v81, s[0:1]
	v_mov_b32_e32 v69, v73
	v_mov_b32_e32 v73, v75
	v_mov_b32_e32 v77, v74
	v_pk_mul_f32 v[80:81], v[68:69], v[72:73]
	v_mov_b32_e32 v72, v232
	v_mov_b32_e32 v73, v233
	v_mov_b32_e32 v74, v234
	v_mov_b32_e32 v75, v235
	v_cndmask_b32_e64 v68, v85, -v85, s[0:1]
	v_mov_b32_e32 v85, v71
	v_mov_b32_e32 v71, v68
	s_waitcnt vmcnt(0) lgkmcnt(0)
	v_mov_b32_e32 v82, v73
	v_mov_b32_e32 v73, v75
	v_pk_mul_f32 v[72:73], v[70:71], v[72:73]
	v_mov_b32_e32 v68, v236
	v_mov_b32_e32 v69, v237
	v_mov_b32_e32 v70, v238
	v_mov_b32_e32 v71, v239
	v_mov_b32_e32 v83, v74
	s_waitcnt vmcnt(0) lgkmcnt(0)
	v_mov_b32_e32 v74, v69
	v_cndmask_b32_e64 v69, v87, -v87, s[0:1]
	v_mov_b32_e32 v87, v65
	v_mov_b32_e32 v65, v69
	v_mov_b32_e32 v69, v71
	v_mov_b32_e32 v75, v70
	v_pk_mul_f32 v[64:65], v[64:65], v[68:69]
	v_mov_b32_e32 v68, v240
	v_mov_b32_e32 v69, v241
	v_mov_b32_e32 v70, v242
	v_mov_b32_e32 v71, v243
	v_pk_fma_f32 v[64:65], v[86:87], v[74:75], v[64:65]
	s_waitcnt vmcnt(0) lgkmcnt(0)
	v_mul_f32_e32 v66, v66, v68
	v_cndmask_b32_e64 v68, v91, -v91, s[0:1]
	v_mul_f32_e32 v92, v68, v69
	v_cndmask_b32_e64 v69, v96, -v96, s[0:1]
	v_mov_b32_e32 v68, v67
	v_pk_mul_f32 v[68:69], v[68:69], v[70:71]
	v_pk_fma_f32 v[70:71], v[84:85], v[82:83], v[72:73]
	v_mov_b32_e32 v67, v68
	v_mov_b32_e32 v93, v69
	v_pk_fma_f32 v[68:69], v[78:79], v[76:77], v[80:81]
	v_pk_add_f32 v[66:67], v[66:67], v[92:93]

; DI unsigned pk2(float a, float b) { hwf32x2 f = {a, b}; hwbf16x2 r = __builtin_convertvector(f, hwbf16x2); return __builtin_bit_cast(unsigned, r); }
;   DI void operator()(int mt, int nt, int wm, int wn, int r, int h, f32x16 (&acc)[WM][2]) const {
;     ...
;           if (ropemode != 0) {
;             const int pc = (ropemode == 1) ? (cc ^ 1) : (cc ^ 2);
;             const float4 p0 = *(const float4*)(T + lr * LD + pc * 8), p1 = *(const float4*)(T + lr * LD + pc * 8 + 4);
;             const float4 c0 = *(const float4*)(bias + nt * 128 + pc * 8), c1 = *(const float4*)(bias + nt * 128 + pc * 8 + 4);
;             const float pr[8] = {p0.x + c0.x, p0.y + c0.y, p0.z + c0.z, p0.w + c0.w, p1.x + c1.x, p1.y + c1.y, p1.z + c1.z, p1.w + c1.w};
;             const int tok = t - NCTX;
;             const int q = (ropemode == 1) ? (cc & 3) : ((cc & 7) >> 1);
;             const int pos = (q < 2) ? (tok >> 6) : (tok & 63);
;             const float2* tab = (ropemode == 1) ? (T32 + pos * 8) : (T64 + pos * 16 + (cc & 1) * 8);
;             const float sgn = (q & 1) ? 1.f : -1.f;
; #pragma unroll
;             for (int k = 0; k < 8; ++k) { const float2 cs = tab[k]; v[k] = v[k] * cs.x + sgn * pr[k] * cs.y; }
;           }
;           *(uint4*)(P + (size_t)row * PW + col0) = make_uint4(pk2(v[0], v[1]), pk2(v[2], v[3]), pk2(v[4], v[5]), pk2(v[6], v[7]));
.LBB0_195:
	global_load_dwordx4 v[228:231], v[92:93], off
	global_load_dwordx4 v[232:235], v[92:93], off offset:16
	global_load_dwordx4 v[236:239], v[92:93], off offset:32
	global_load_dwordx4 v[240:243], v[92:93], off offset:48
	s_waitcnt vmcnt(0) lgkmcnt(1)
	v_add_f32_e32 v80, v84, v80
	v_add_f32_e32 v81, v85, v81
	v_add_f32_e32 v84, v86, v82
	v_add_f32_e32 v85, v87, v83
	s_waitcnt lgkmcnt(0)
	v_add_f32_e32 v86, v76, v72
	v_add_f32_e32 v87, v77, v73
	v_add_f32_e32 v91, v78, v74
	v_add_f32_e32 v97, v79, v75
	v_mov_b32_e32 v72, v228
	v_mov_b32_e32 v73, v229
	v_mov_b32_e32 v74, v230
	v_mov_b32_e32 v75, v231
	v_mov_b32_e32 v79, v69
	v_cndmask_b32_e64 v78, v80, -v80, s[0:1]
	v_cndmask_b32_e64 v84, v84, -v84, s[0:1]
	v_cndmask_b32_e64 v86, v86, -v86, s[0:1]
	s_waitcnt vmcnt(0) lgkmcnt(0)
	v_mov_b32_e32 v76, v73
	v_cndmask_b32_e64 v73, v81, -v81, s[0:1]
	v_mov_b32_e32 v69, v73
	v_mov_b32_e32 v73, v75
	v_mov_b32_e32 v77, v74
	v_pk_mul_f32 v[80:81], v[68:69], v[72:73]
	v_mov_b32_e32 v72, v232
	v_mov_b32_e32 v73, v233
	v_mov_b32_e32 v74, v234
	v_mov_b32_e32 v75, v235
	v_cndmask_b32_e64 v68, v85, -v85, s[0:1]
	v_mov_b32_e32 v85, v71
	v_mov_b32_e32 v71, v68
	s_waitcnt vmcnt(0) lgkmcnt(0)
	v_mov_b32_e32 v82, v73
	v_mov_b32_e32 v73, v75
	v_pk_mul_f32 v[72:73], v[70:71], v[72:73]
	v_mov_b32_e32 v68, v236
	v_mov_b32_e32 v69, v237
	v_mov_b32_e32 v70, v238
	v_mov_b32_e32 v71, v239
	v_mov_b32_e32 v83, v74
	s_waitcnt vmcnt(0) lgkmcnt(0)
	v_mov_b32_e32 v74, v69
	v_cndmask_b32_e64 v69, v87, -v87, s[0:1]
	v_mov_b32_e32 v87, v65
	v_mov_b32_e32 v65, v69
	v_mov_b32_e32 v69, v71
	v_mov_b32_e32 v75, v70
	v_pk_mul_f32 v[64:65], v[64:65], v[68:69]
	v_mov_b32_e32 v68, v240
	v_mov_b32_e32 v69, v241
	v_mov_b32_e32 v70, v242
	v_mov_b32_e32 v71, v243
	v_pk_fma_f32 v[64:65], v[86:87], v[74:75], v[64:65]
	s_waitcnt vmcnt(0) lgkmcnt(0)
	v_mul_f32_e32 v66, v66, v68
	v_cndmask_b32_e64 v68, v91, -v91, s[0:1]
	v_mul_f32_e32 v92, v68, v69
	v_cndmask_b32_e64 v69, v97, -v97, s[0:1]
	v_mov_b32_e32 v68, v67
	v_pk_mul_f32 v[68:69], v[68:69], v[70:71]
	v_pk_fma_f32 v[70:71], v[84:85], v[82:83], v[72:73]
	v_mov_b32_e32 v67, v68
	v_mov_b32_e32 v93, v69
	v_pk_fma_f32 v[68:69], v[78:79], v[76:77], v[80:81]
	v_pk_add_f32 v[66:67], v[66:67], v[92:93]

; DI unsigned pk2(float a, float b) { hwf32x2 f = {a, b}; hwbf16x2 r = __builtin_convertvector(f, hwbf16x2); return __builtin_bit_cast(unsigned, r); }
;   DI void operator()(int mt, int nt, int wm, int wn, int r, int h, f32x16 (&acc)[WM][2]) const {
;     ...
;           if (ropemode != 0) {
;             const int pc = (ropemode == 1) ? (cc ^ 1) : (cc ^ 2);
;             const float4 p0 = *(const float4*)(T + lr * LD + pc * 8), p1 = *(const float4*)(T + lr * LD + pc * 8 + 4);
;             const float4 c0 = *(const float4*)(bias + nt * 128 + pc * 8), c1 = *(const float4*)(bias + nt * 128 + pc * 8 + 4);
;             const float pr[8] = {p0.x + c0.x, p0.y + c0.y, p0.z + c0.z, p0.w + c0.w, p1.x + c1.x, p1.y + c1.y, p1.z + c1.z, p1.w + c1.w};
;             const int tok = t - NCTX;
;             const int q = (ropemode == 1) ? (cc & 3) : ((cc & 7) >> 1);
;             const int pos = (q < 2) ? (tok >> 6) : (tok & 63);
;             const float2* tab = (ropemode == 1) ? (T32 + pos * 8) : (T64 + pos * 16 + (cc & 1) * 8);
;             const float sgn = (q & 1) ? 1.f : -1.f;
; #pragma unroll
;             for (int k = 0; k < 8; ++k) { const float2 cs = tab[k]; v[k] = v[k] * cs.x + sgn * pr[k] * cs.y; }
;           }
;           *(uint4*)(P + (size_t)row * PW + col0) = make_uint4(pk2(v[0], v[1]), pk2(v[2], v[3]), pk2(v[4], v[5]), pk2(v[6], v[7]));
.LBB0_204:
	global_load_dwordx4 v[228:231], v[92:93], off
	global_load_dwordx4 v[232:235], v[92:93], off offset:16
	global_load_dwordx4 v[236:239], v[92:93], off offset:32
	global_load_dwordx4 v[240:243], v[92:93], off offset:48
	s_waitcnt vmcnt(0) lgkmcnt(1)
	v_add_f32_e32 v80, v84, v80
	v_add_f32_e32 v81, v85, v81
	v_add_f32_e32 v84, v86, v82
	v_add_f32_e32 v85, v87, v83
	s_waitcnt lgkmcnt(0)
	v_add_f32_e32 v86, v76, v72
	v_add_f32_e32 v87, v77, v73
	v_add_f32_e32 v91, v78, v74
	v_add_f32_e32 v98, v79, v75
	v_mov_b32_e32 v72, v228
	v_mov_b32_e32 v73, v229
	v_mov_b32_e32 v74, v230
	v_mov_b32_e32 v75, v231
	v_mov_b32_e32 v79, v69
	v_cndmask_b32_e64 v78, v80, -v80, s[0:1]
	v_cndmask_b32_e64 v84, v84, -v84, s[0:1]
	v_cndmask_b32_e64 v86, v86, -v86, s[0:1]
	s_waitcnt vmcnt(0) lgkmcnt(0)
	v_mov_b32_e32 v76, v73
	v_cndmask_b32_e64 v73, v81, -v81, s[0:1]
	v_mov_b32_e32 v69, v73
	v_mov_b32_e32 v73, v75
	v_mov_b32_e32 v77, v74
	v_pk_mul_f32 v[80:81], v[68:69], v[72:73]
	v_mov_b32_e32 v72, v232
	v_mov_b32_e32 v73, v233
	v_mov_b32_e32 v74, v234
	v_mov_b32_e32 v75, v235
	v_cndmask_b32_e64 v68, v85, -v85, s[0:1]
	v_mov_b32_e32 v85, v71
	v_mov_b32_e32 v71, v68
	s_waitcnt vmcnt(0) lgkmcnt(0)
	v_mov_b32_e32 v82, v73
	v_mov_b32_e32 v73, v75
	v_pk_mul_f32 v[72:73], v[70:71], v[72:73]
	v_mov_b32_e32 v68, v236
	v_mov_b32_e32 v69, v237
	v_mov_b32_e32 v70, v238
	v_mov_b32_e32 v71, v239
	v_mov_b32_e32 v83, v74
	s_waitcnt vmcnt(0) lgkmcnt(0)
	v_mov_b32_e32 v74, v69
	v_cndmask_b32_e64 v69, v87, -v87, s[0:1]
	v_mov_b32_e32 v87, v65
	v_mov_b32_e32 v65, v69
	v_mov_b32_e32 v69, v71
	v_mov_b32_e32 v75, v70
	v_pk_mul_f32 v[64:65], v[64:65], v[68:69]
	v_mov_b32_e32 v68, v240
	v_mov_b32_e32 v69, v241
	v_mov_b32_e32 v70, v242
	v_mov_b32_e32 v71, v243
	v_pk_fma_f32 v[64:65], v[86:87], v[74:75], v[64:65]
	s_waitcnt vmcnt(0) lgkmcnt(0)
	v_mul_f32_e32 v66, v66, v68
	v_cndmask_b32_e64 v68, v91, -v91, s[0:1]
	v_mul_f32_e32 v92, v68, v69
	v_cndmask_b32_e64 v69, v98, -v98, s[0:1]
	v_mov_b32_e32 v68, v67
	v_pk_mul_f32 v[68:69], v[68:69], v[70:71]
	v_pk_fma_f32 v[70:71], v[84:85], v[82:83], v[72:73]
	v_mov_b32_e32 v67, v68
	v_mov_b32_e32 v93, v69
	v_pk_fma_f32 v[68:69], v[78:79], v[76:77], v[80:81]
	v_pk_add_f32 v[66:67], v[66:67], v[92:93]

; DI unsigned pk2(float a, float b) { hwf32x2 f = {a, b}; hwbf16x2 r = __builtin_convertvector(f, hwbf16x2); return __builtin_bit_cast(unsigned, r); }
;   DI void operator()(int mt, int nt, int wm, int wn, int r, int h, f32x16 (&acc)[WM][2]) const {
;     ...
;           if (ropemode != 0) {
;             const int pc = (ropemode == 1) ? (cc ^ 1) : (cc ^ 2);
;             const float4 p0 = *(const float4*)(T + lr * LD + pc * 8), p1 = *(const float4*)(T + lr * LD + pc * 8 + 4);
;             const float4 c0 = *(const float4*)(bias + nt * 128 + pc * 8), c1 = *(const float4*)(bias + nt * 128 + pc * 8 + 4);
;             const float pr[8] = {p0.x + c0.x, p0.y + c0.y, p0.z + c0.z, p0.w + c0.w, p1.x + c1.x, p1.y + c1.y, p1.z + c1.z, p1.w + c1.w};
;             const int tok = t - NCTX;
;             const int q = (ropemode == 1) ? (cc & 3) : ((cc & 7) >> 1);
;             const int pos = (q < 2) ? (tok >> 6) : (tok & 63);
;             const float2* tab = (ropemode == 1) ? (T32 + pos * 8) : (T64 + pos * 16 + (cc & 1) * 8);
;             const float sgn = (q & 1) ? 1.f : -1.f;
; #pragma unroll
;             for (int k = 0; k < 8; ++k) { const float2 cs = tab[k]; v[k] = v[k] * cs.x + sgn * pr[k] * cs.y; }
;           }
;           *(uint4*)(P + (size_t)row * PW + col0) = make_uint4(pk2(v[0], v[1]), pk2(v[2], v[3]), pk2(v[4], v[5]), pk2(v[6], v[7]));
.LBB0_213:
	global_load_dwordx4 v[228:231], v[92:93], off
	global_load_dwordx4 v[232:235], v[92:93], off offset:16
	global_load_dwordx4 v[236:239], v[92:93], off offset:32
	global_load_dwordx4 v[240:243], v[92:93], off offset:48
	s_waitcnt vmcnt(0) lgkmcnt(1)
	v_add_f32_e32 v80, v84, v80
	v_add_f32_e32 v81, v85, v81
	v_add_f32_e32 v84, v86, v82
	v_add_f32_e32 v85, v87, v83
	s_waitcnt lgkmcnt(0)
	v_add_f32_e32 v86, v76, v72
	v_add_f32_e32 v87, v77, v73
	v_add_f32_e32 v91, v78, v74
	v_add_f32_e32 v99, v79, v75
	v_mov_b32_e32 v72, v228
	v_mov_b32_e32 v73, v229
	v_mov_b32_e32 v74, v230
	v_mov_b32_e32 v75, v231
	v_mov_b32_e32 v79, v69
	v_cndmask_b32_e64 v78, v80, -v80, s[0:1]
	v_cndmask_b32_e64 v84, v84, -v84, s[0:1]
	v_cndmask_b32_e64 v86, v86, -v86, s[0:1]
	s_waitcnt vmcnt(0) lgkmcnt(0)
	v_mov_b32_e32 v76, v73
	v_cndmask_b32_e64 v73, v81, -v81, s[0:1]
	v_mov_b32_e32 v69, v73
	v_mov_b32_e32 v73, v75
	v_mov_b32_e32 v77, v74
	v_pk_mul_f32 v[80:81], v[68:69], v[72:73]
	v_mov_b32_e32 v72, v232
	v_mov_b32_e32 v73, v233
	v_mov_b32_e32 v74, v234
	v_mov_b32_e32 v75, v235
	v_cndmask_b32_e64 v68, v85, -v85, s[0:1]
	v_mov_b32_e32 v85, v71
	v_mov_b32_e32 v71, v68
	s_waitcnt vmcnt(0) lgkmcnt(0)
	v_mov_b32_e32 v82, v73
	v_mov_b32_e32 v73, v75
	v_pk_mul_f32 v[72:73], v[70:71], v[72:73]
	v_mov_b32_e32 v68, v236
	v_mov_b32_e32 v69, v237
	v_mov_b32_e32 v70, v238
	v_mov_b32_e32 v71, v239
	v_mov_b32_e32 v83, v74
	s_waitcnt vmcnt(0) lgkmcnt(0)
	v_mov_b32_e32 v74, v69
	v_cndmask_b32_e64 v69, v87, -v87, s[0:1]
	v_mov_b32_e32 v87, v65
	v_mov_b32_e32 v65, v69
	v_mov_b32_e32 v69, v71
	v_mov_b32_e32 v75, v70
	v_pk_mul_f32 v[64:65], v[64:65], v[68:69]
	v_mov_b32_e32 v68, v240
	v_mov_b32_e32 v69, v241
	v_mov_b32_e32 v70, v242
	v_mov_b32_e32 v71, v243
	v_pk_fma_f32 v[64:65], v[86:87], v[74:75], v[64:65]
	s_waitcnt vmcnt(0) lgkmcnt(0)
	v_mul_f32_e32 v66, v66, v68
	v_cndmask_b32_e64 v68, v91, -v91, s[0:1]
	v_mul_f32_e32 v92, v68, v69
	v_cndmask_b32_e64 v69, v99, -v99, s[0:1]
	v_mov_b32_e32 v68, v67
	v_pk_mul_f32 v[68:69], v[68:69], v[70:71]
	v_pk_fma_f32 v[70:71], v[84:85], v[82:83], v[72:73]
	v_mov_b32_e32 v67, v68
	v_mov_b32_e32 v93, v69
	v_pk_fma_f32 v[68:69], v[78:79], v[76:77], v[80:81]
	v_pk_add_f32 v[66:67], v[66:67], v[92:93]

; DI unsigned pk2(float a, float b) { hwf32x2 f = {a, b}; hwbf16x2 r = __builtin_convertvector(f, hwbf16x2); return __builtin_bit_cast(unsigned, r); }
;   DI void operator()(int mt, int nt, int wm, int wn, int r, int h, f32x16 (&acc)[WM][2]) const {
;     ...
;           if (ropemode != 0) {
;             const int pc = (ropemode == 1) ? (cc ^ 1) : (cc ^ 2);
;             const float4 p0 = *(const float4*)(T + lr * LD + pc * 8), p1 = *(const float4*)(T + lr * LD + pc * 8 + 4);
;             const float4 c0 = *(const float4*)(bias + nt * 128 + pc * 8), c1 = *(const float4*)(bias + nt * 128 + pc * 8 + 4);
;             const float pr[8] = {p0.x + c0.x, p0.y + c0.y, p0.z + c0.z, p0.w + c0.w, p1.x + c1.x, p1.y + c1.y, p1.z + c1.z, p1.w + c1.w};
;             const int tok = t - NCTX;
;             const int q = (ropemode == 1) ? (cc & 3) : ((cc & 7) >> 1);
;             const int pos = (q < 2) ? (tok >> 6) : (tok & 63);
;             const float2* tab = (ropemode == 1) ? (T32 + pos * 8) : (T64 + pos * 16 + (cc & 1) * 8);
;             const float sgn = (q & 1) ? 1.f : -1.f;
; #pragma unroll
;             for (int k = 0; k < 8; ++k) { const float2 cs = tab[k]; v[k] = v[k] * cs.x + sgn * pr[k] * cs.y; }
;           }
;           *(uint4*)(P + (size_t)row * PW + col0) = make_uint4(pk2(v[0], v[1]), pk2(v[2], v[3]), pk2(v[4], v[5]), pk2(v[6], v[7]));
.LBB0_222:
	global_load_dwordx4 v[228:231], v[92:93], off
	global_load_dwordx4 v[232:235], v[92:93], off offset:16
	global_load_dwordx4 v[236:239], v[92:93], off offset:32
	global_load_dwordx4 v[240:243], v[92:93], off offset:48
	s_waitcnt vmcnt(0) lgkmcnt(1)
	v_add_f32_e32 v80, v84, v80
	v_add_f32_e32 v81, v85, v81
	v_add_f32_e32 v84, v86, v82
	v_add_f32_e32 v85, v87, v83
	s_waitcnt lgkmcnt(0)
	v_add_f32_e32 v86, v76, v72
	v_add_f32_e32 v87, v77, v73
	v_add_f32_e32 v91, v78, v74
	v_add_f32_e32 v100, v79, v75
	v_mov_b32_e32 v72, v228
	v_mov_b32_e32 v73, v229
	v_mov_b32_e32 v74, v230
	v_mov_b32_e32 v75, v231
	v_mov_b32_e32 v79, v69
	v_cndmask_b32_e64 v78, v80, -v80, s[0:1]
	v_cndmask_b32_e64 v84, v84, -v84, s[0:1]
	v_cndmask_b32_e64 v86, v86, -v86, s[0:1]
	s_waitcnt vmcnt(0) lgkmcnt(0)
	v_mov_b32_e32 v76, v73
	v_cndmask_b32_e64 v73, v81, -v81, s[0:1]
	v_mov_b32_e32 v69, v73
	v_mov_b32_e32 v73, v75
	v_mov_b32_e32 v77, v74
	v_pk_mul_f32 v[80:81], v[68:69], v[72:73]
	v_mov_b32_e32 v72, v232
	v_mov_b32_e32 v73, v233
	v_mov_b32_e32 v74, v234
	v_mov_b32_e32 v75, v235
	v_cndmask_b32_e64 v68, v85, -v85, s[0:1]
	v_mov_b32_e32 v85, v71
	v_mov_b32_e32 v71, v68
	s_waitcnt vmcnt(0) lgkmcnt(0)
	v_mov_b32_e32 v82, v73
	v_mov_b32_e32 v73, v75
	v_pk_mul_f32 v[72:73], v[70:71], v[72:73]
	v_mov_b32_e32 v68, v236
	v_mov_b32_e32 v69, v237
	v_mov_b32_e32 v70, v238
	v_mov_b32_e32 v71, v239
	v_mov_b32_e32 v83, v74
	s_waitcnt vmcnt(0) lgkmcnt(0)
	v_mov_b32_e32 v74, v69
	v_cndmask_b32_e64 v69, v87, -v87, s[0:1]
	v_mov_b32_e32 v87, v65
	v_mov_b32_e32 v65, v69
	v_mov_b32_e32 v69, v71
	v_mov_b32_e32 v75, v70
	v_pk_mul_f32 v[64:65], v[64:65], v[68:69]
	v_mov_b32_e32 v68, v240
	v_mov_b32_e32 v69, v241
	v_mov_b32_e32 v70, v242
	v_mov_b32_e32 v71, v243
	v_pk_fma_f32 v[64:65], v[86:87], v[74:75], v[64:65]
	s_waitcnt vmcnt(0) lgkmcnt(0)
	v_mul_f32_e32 v66, v66, v68
	v_cndmask_b32_e64 v68, v91, -v91, s[0:1]
	v_mul_f32_e32 v92, v68, v69
	v_cndmask_b32_e64 v69, v100, -v100, s[0:1]
	v_mov_b32_e32 v68, v67
	v_pk_mul_f32 v[68:69], v[68:69], v[70:71]
	v_pk_fma_f32 v[70:71], v[84:85], v[82:83], v[72:73]
	v_mov_b32_e32 v67, v68
	v_mov_b32_e32 v93, v69
	v_pk_fma_f32 v[68:69], v[78:79], v[76:77], v[80:81]
	v_pk_add_f32 v[66:67], v[66:67], v[92:93]

; DI unsigned pk2(float a, float b) { hwf32x2 f = {a, b}; hwbf16x2 r = __builtin_convertvector(f, hwbf16x2); return __builtin_bit_cast(unsigned, r); }
;   DI void operator()(int mt, int nt, int wm, int wn, int r, int h, f32x16 (&acc)[WM][2]) const {
;     ...
;           if (ropemode != 0) {
;             const int pc = (ropemode == 1) ? (cc ^ 1) : (cc ^ 2);
;             const float4 p0 = *(const float4*)(T + lr * LD + pc * 8), p1 = *(const float4*)(T + lr * LD + pc * 8 + 4);
;             const float4 c0 = *(const float4*)(bias + nt * 128 + pc * 8), c1 = *(const float4*)(bias + nt * 128 + pc * 8 + 4);
;             const float pr[8] = {p0.x + c0.x, p0.y + c0.y, p0.z + c0.z, p0.w + c0.w, p1.x + c1.x, p1.y + c1.y, p1.z + c1.z, p1.w + c1.w};
;             const int tok = t - NCTX;
;             const int q = (ropemode == 1) ? (cc & 3) : ((cc & 7) >> 1);
;             const int pos = (q < 2) ? (tok >> 6) : (tok & 63);
;             const float2* tab = (ropemode == 1) ? (T32 + pos * 8) : (T64 + pos * 16 + (cc & 1) * 8);
;             const float sgn = (q & 1) ? 1.f : -1.f;
; #pragma unroll
;             for (int k = 0; k < 8; ++k) { const float2 cs = tab[k]; v[k] = v[k] * cs.x + sgn * pr[k] * cs.y; }
;           }
;           *(uint4*)(P + (size_t)row * PW + col0) = make_uint4(pk2(v[0], v[1]), pk2(v[2], v[3]), pk2(v[4], v[5]), pk2(v[6], v[7]));
.LBB0_231:
	global_load_dwordx4 v[228:231], v[92:93], off
	global_load_dwordx4 v[232:235], v[92:93], off offset:16
	global_load_dwordx4 v[236:239], v[92:93], off offset:32
	global_load_dwordx4 v[240:243], v[92:93], off offset:48
	s_waitcnt vmcnt(0) lgkmcnt(1)
	v_add_f32_e32 v80, v84, v80
	v_add_f32_e32 v81, v85, v81
	v_add_f32_e32 v84, v86, v82
	v_add_f32_e32 v85, v87, v83
	s_waitcnt lgkmcnt(0)
	v_add_f32_e32 v86, v76, v72
	v_add_f32_e32 v87, v77, v73
	v_add_f32_e32 v91, v78, v74
	v_add_f32_e32 v101, v79, v75
	v_mov_b32_e32 v72, v228
	v_mov_b32_e32 v73, v229
	v_mov_b32_e32 v74, v230
	v_mov_b32_e32 v75, v231
	v_mov_b32_e32 v79, v69
	v_cndmask_b32_e64 v78, v80, -v80, s[0:1]
	v_cndmask_b32_e64 v84, v84, -v84, s[0:1]
	v_cndmask_b32_e64 v86, v86, -v86, s[0:1]
	s_waitcnt vmcnt(0) lgkmcnt(0)
	v_mov_b32_e32 v76, v73
	v_cndmask_b32_e64 v73, v81, -v81, s[0:1]
	v_mov_b32_e32 v69, v73
	v_mov_b32_e32 v73, v75
	v_mov_b32_e32 v77, v74
	v_pk_mul_f32 v[80:81], v[68:69], v[72:73]
	v_mov_b32_e32 v72, v232
	v_mov_b32_e32 v73, v233
	v_mov_b32_e32 v74, v234
	v_mov_b32_e32 v75, v235
	v_cndmask_b32_e64 v68, v85, -v85, s[0:1]
	v_mov_b32_e32 v85, v71
	v_mov_b32_e32 v71, v68
	s_waitcnt vmcnt(0) lgkmcnt(0)
	v_mov_b32_e32 v82, v73
	v_mov_b32_e32 v73, v75
	v_pk_mul_f32 v[72:73], v[70:71], v[72:73]
	v_mov_b32_e32 v68, v236
	v_mov_b32_e32 v69, v237
	v_mov_b32_e32 v70, v238
	v_mov_b32_e32 v71, v239
	v_mov_b32_e32 v83, v74
	s_waitcnt vmcnt(0) lgkmcnt(0)
	v_mov_b32_e32 v74, v69
	v_cndmask_b32_e64 v69, v87, -v87, s[0:1]
	v_mov_b32_e32 v87, v65
	v_mov_b32_e32 v65, v69
	v_mov_b32_e32 v69, v71
	v_mov_b32_e32 v75, v70
	v_pk_mul_f32 v[64:65], v[64:65], v[68:69]
	v_mov_b32_e32 v68, v240
	v_mov_b32_e32 v69, v241
	v_mov_b32_e32 v70, v242
	v_mov_b32_e32 v71, v243
	v_pk_fma_f32 v[64:65], v[86:87], v[74:75], v[64:65]
	s_waitcnt vmcnt(0) lgkmcnt(0)
	v_mul_f32_e32 v66, v66, v68
	v_cndmask_b32_e64 v68, v91, -v91, s[0:1]
	v_mul_f32_e32 v92, v68, v69
	v_cndmask_b32_e64 v69, v101, -v101, s[0:1]
	v_mov_b32_e32 v68, v67
	v_pk_mul_f32 v[68:69], v[68:69], v[70:71]
	v_pk_fma_f32 v[70:71], v[84:85], v[82:83], v[72:73]
	v_mov_b32_e32 v67, v68
	v_mov_b32_e32 v93, v69
	v_pk_fma_f32 v[68:69], v[78:79], v[76:77], v[80:81]
	v_pk_add_f32 v[66:67], v[66:67], v[92:93]

; DI unsigned pk2(float a, float b) { hwf32x2 f = {a, b}; hwbf16x2 r = __builtin_convertvector(f, hwbf16x2); return __builtin_bit_cast(unsigned, r); }
;   DI void operator()(int mt, int nt, int wm, int wn, int r, int h, f32x16 (&acc)[WM][2]) const {
;     ...
;           if (ropemode != 0) {
;             const int pc = (ropemode == 1) ? (cc ^ 1) : (cc ^ 2);
;             const float4 p0 = *(const float4*)(T + lr * LD + pc * 8), p1 = *(const float4*)(T + lr * LD + pc * 8 + 4);
;             const float4 c0 = *(const float4*)(bias + nt * 128 + pc * 8), c1 = *(const float4*)(bias + nt * 128 + pc * 8 + 4);
;             const float pr[8] = {p0.x + c0.x, p0.y + c0.y, p0.z + c0.z, p0.w + c0.w, p1.x + c1.x, p1.y + c1.y, p1.z + c1.z, p1.w + c1.w};
;             const int tok = t - NCTX;
;             const int q = (ropemode == 1) ? (cc & 3) : ((cc & 7) >> 1);
;             const int pos = (q < 2) ? (tok >> 6) : (tok & 63);
;             const float2* tab = (ropemode == 1) ? (T32 + pos * 8) : (T64 + pos * 16 + (cc & 1) * 8);
;             const float sgn = (q & 1) ? 1.f : -1.f;
; #pragma unroll
;             for (int k = 0; k < 8; ++k) { const float2 cs = tab[k]; v[k] = v[k] * cs.x + sgn * pr[k] * cs.y; }
;           }
;           *(uint4*)(P + (size_t)row * PW + col0) = make_uint4(pk2(v[0], v[1]), pk2(v[2], v[3]), pk2(v[4], v[5]), pk2(v[6], v[7]));
.LBB0_240:
	global_load_dwordx4 v[228:231], v[92:93], off
	global_load_dwordx4 v[232:235], v[92:93], off offset:16
	global_load_dwordx4 v[236:239], v[92:93], off offset:32
	global_load_dwordx4 v[240:243], v[92:93], off offset:48
	s_waitcnt vmcnt(0) lgkmcnt(1)
	v_add_f32_e32 v80, v84, v80
	v_add_f32_e32 v81, v85, v81
	v_add_f32_e32 v84, v86, v82
	v_add_f32_e32 v85, v87, v83
	s_waitcnt lgkmcnt(0)
	v_add_f32_e32 v86, v76, v72
	v_add_f32_e32 v87, v77, v73
	v_add_f32_e32 v91, v78, v74
	v_add_f32_e32 v160, v79, v75
	v_mov_b32_e32 v72, v228
	v_mov_b32_e32 v73, v229
	v_mov_b32_e32 v74, v230
	v_mov_b32_e32 v75, v231
	v_mov_b32_e32 v79, v69
	v_cndmask_b32_e64 v78, v80, -v80, s[0:1]
	v_cndmask_b32_e64 v84, v84, -v84, s[0:1]
	v_cndmask_b32_e64 v86, v86, -v86, s[0:1]
	s_waitcnt vmcnt(0) lgkmcnt(0)
	v_mov_b32_e32 v76, v73
	v_cndmask_b32_e64 v73, v81, -v81, s[0:1]
	v_mov_b32_e32 v69, v73
	v_mov_b32_e32 v73, v75
	v_mov_b32_e32 v77, v74
	v_pk_mul_f32 v[80:81], v[68:69], v[72:73]
	v_mov_b32_e32 v72, v232
	v_mov_b32_e32 v73, v233
	v_mov_b32_e32 v74, v234
	v_mov_b32_e32 v75, v235
	v_cndmask_b32_e64 v68, v85, -v85, s[0:1]
	v_mov_b32_e32 v85, v71
	v_mov_b32_e32 v71, v68
	s_waitcnt vmcnt(0) lgkmcnt(0)
	v_mov_b32_e32 v82, v73
	v_mov_b32_e32 v73, v75
	v_pk_mul_f32 v[72:73], v[70:71], v[72:73]
	v_mov_b32_e32 v68, v236
	v_mov_b32_e32 v69, v237
	v_mov_b32_e32 v70, v238
	v_mov_b32_e32 v71, v239
	v_mov_b32_e32 v83, v74
	s_waitcnt vmcnt(0) lgkmcnt(0)
	v_mov_b32_e32 v74, v69
	v_cndmask_b32_e64 v69, v87, -v87, s[0:1]
	v_mov_b32_e32 v87, v65
	v_mov_b32_e32 v65, v69
	v_mov_b32_e32 v69, v71
	v_mov_b32_e32 v75, v70
	v_pk_mul_f32 v[64:65], v[64:65], v[68:69]
	v_mov_b32_e32 v68, v240
	v_mov_b32_e32 v69, v241
	v_mov_b32_e32 v70, v242
	v_mov_b32_e32 v71, v243
	v_pk_fma_f32 v[64:65], v[86:87], v[74:75], v[64:65]
	s_waitcnt vmcnt(0) lgkmcnt(0)
	v_mul_f32_e32 v66, v66, v68
	v_cndmask_b32_e64 v68, v91, -v91, s[0:1]
	v_mul_f32_e32 v92, v68, v69
	v_cndmask_b32_e64 v69, v160, -v160, s[0:1]
	v_mov_b32_e32 v68, v67
	v_pk_mul_f32 v[68:69], v[68:69], v[70:71]
	v_pk_fma_f32 v[70:71], v[84:85], v[82:83], v[72:73]
	v_mov_b32_e32 v67, v68
	v_mov_b32_e32 v93, v69
	v_pk_fma_f32 v[68:69], v[78:79], v[76:77], v[80:81]
	v_pk_add_f32 v[66:67], v[66:67], v[92:93]

;   DI void operator()(int mt, int nt, int wm, int wn, int r, int h, f32x16 (&acc)[WM][2]) const {
;     ...
;       if (nt == 4 || nt == 5 || nt == 17) {
; #pragma unroll
;         for (int j = 0; j < 8; ++j) {
;           const int id = tid + 256 * j;
;           const int c = id & 127, rg = id >> 7;
;           const int lr0 = rg * 8;
;           const int row = mt * (WM * 64) + (lr0 >> 6) * (WM * 32) + ps * 64 + (lr0 & 63);
;           const int b = row / NTOK, t = row % NTOK;
;           const int col = nt * 128 + c;
;           const float bb = bias[col];
;           float x[8];
; #pragma unroll
;           for (int k = 0; k < 8; ++k) x[k] = T[(lr0 + k) * LD + c] + bb;
.LBB0_247:
	v_and_b32_e32 v66, 0x7f, v204
	v_or_b32_e32 v160, s24, v66
	v_add_u32_e32 v64, 0xfffffe00, v160
	v_ashrrev_i32_e32 v65, 31, v64
	v_add_u32_e32 v67, 0xfffff780, v160
	s_andn2_b64 vcc, exec, s[8:9]
	v_lshlrev_b32_e32 v66, 2, v66
	v_and_b32_e32 v85, 0xffffff8, v94
	v_lshl_add_u64 v[68:69], v[160:161], 2, s[14:15]
	v_or_b32_e32 v84, 7, v94
	s_cbranch_vccnz .LBB0_281
	global_load_dword v244, v[68:69], off
	v_and_or_b32 v73, v94, 56, v205
	v_mul_hi_i32 v70, v73, s55
	v_lshrrev_b32_e32 v71, 31, v70
	v_ashrrev_i32_e32 v70, 9, v70
	v_mad_u64_u32 v[74:75], s[8:9], v85, s66, v[66:67]
	v_add_u32_e32 v70, v70, v71
	v_add_u32_e32 v71, 0x400, v74
	ds_read2_b32 v[78:79], v71 offset0:8 offset1:140
	v_add_u32_e32 v71, 0x800, v74
	v_mad_u64_u32 v[82:83], s[8:9], v84, s66, v[66:67]
	ds_read2_b32 v[76:77], v74 offset1:132
	ds_read2_b32 v[80:81], v71 offset0:16 offset1:148
	ds_read_b32 v74, v74 offset:3168
	ds_read_b32 v75, v82
	v_ashrrev_i32_e32 v71, 31, v70
	s_mov_b64 s[8:9], -1
	s_and_b64 vcc, exec, s[20:21]
	s_cbranch_vccz .LBB0_250
	v_lshlrev_b64 v[82:83], 8, v[70:71]
	v_lshl_add_u64 v[82:83], v[82:83], 0, v[64:65]
	s_mov_b64 s[8:9], 0

; DI unsigned pk2(float a, float b) { hwf32x2 f = {a, b}; hwbf16x2 r = __builtin_convertvector(f, hwbf16x2); return __builtin_bit_cast(unsigned, r); }
;   DI void operator()(int mt, int nt, int wm, int wn, int r, int h, f32x16 (&acc)[WM][2]) const {
;     ...
;         for (int j = 0; j < 8; ++j) {
;           const int id = tid + 256 * j;
;           const int c = id & 127, rg = id >> 7;
;           const int lr0 = rg * 8;
;           const int row = mt * (WM * 64) + (lr0 >> 6) * (WM * 32) + ps * 64 + (lr0 & 63);
;           const int b = row / NTOK, t = row % NTOK;
;           const int col = nt * 128 + c;
;           const float bb = bias[col];
;           float x[8];
; #pragma unroll
;           for (int k = 0; k < 8; ++k) x[k] = T[(lr0 + k) * LD + c] + bb;
;           bf16_t* vt = (nt == 17) ? VTC + ((size_t)b * 128 + (col - C_V)) * NTOK : VTA + ((size_t)b * 256 + (col - A_V)) * NTOK;
;           *(uint4*)(vt + t) = make_uint4(pk2(x[0], x[1]), pk2(x[2], x[3]), pk2(x[4], x[5]), pk2(x[6], x[7]));
;         }
.LBB0_252:
	s_add_u32 s8, s68, s8
	v_mul_i32_i24_e32 v70, 0x900, v70
	s_addc_u32 s9, s69, s9
	v_sub_u32_e32 v86, v73, v70
	v_mov_b64_e32 v[70:71], s[8:9]
	v_mad_u64_u32 v[90:91], s[8:9], v82, s67, v[70:71]
	v_mov_b32_e32 v70, v91
	v_mad_u64_u32 v[70:71], s[8:9], v83, s67, v[70:71]
	s_waitcnt vmcnt(0) lgkmcnt(0)
	v_mov_b32_e32 v72, v244
	v_pk_add_f32 v[76:77], v[72:73], v[76:77] op_sel_hi:[0,1]
	v_pk_add_f32 v[78:79], v[72:73], v[78:79] op_sel_hi:[0,1]
	v_pk_add_f32 v[80:81], v[72:73], v[80:81] op_sel_hi:[0,1]
	v_pk_add_f32 v[74:75], v[72:73], v[74:75] op_sel_hi:[0,1]
	v_mov_b32_e32 v91, v70
	v_ashrrev_i32_e32 v87, 31, v86
	v_cvt_pk_bf16_f32 v70, v76, v77
	v_cvt_pk_bf16_f32 v71, v78, v79
	v_cvt_pk_bf16_f32 v72, v80, v81
	v_cvt_pk_bf16_f32 v73, v74, v75
	v_lshl_add_u64 v[74:75], v[86:87], 1, v[90:91]
	global_store_dwordx4 v[74:75], v[70:73], off
	s_nop 0
	s_andn2_b64 vcc, exec, s[20:21]
	v_and_b32_e32 v73, 0xffffff8, v95
	v_mad_u64_u32 v[80:81], s[8:9], v73, s66, v[66:67]
	v_and_or_b32 v71, v95, 56, v206
	v_add_u32_e32 v73, 0x400, v80
	v_mul_hi_i32 v72, v71, s55
	ds_read2_b32 v[76:77], v73 offset0:8 offset1:140
	v_add_u32_e32 v73, 0x800, v80
	v_lshrrev_b32_e32 v74, 31, v72
	v_ashrrev_i32_e32 v72, 9, v72
	ds_read2_b32 v[78:79], v73 offset0:16 offset1:148
	v_or_b32_e32 v73, 7, v95
	v_add_u32_e32 v72, v72, v74
	ds_read2_b32 v[74:75], v80 offset1:132
	v_mad_u64_u32 v[82:83], s[8:9], v73, s66, v[66:67]
	ds_read_b32 v80, v80 offset:3168
	ds_read_b32 v81, v82
	v_cndmask_b32_e64 v82, 0, 1, s[20:21]
	v_ashrrev_i32_e32 v73, 31, v72
	v_cmp_ne_u32_e64 s[8:9], 1, v82
	s_mov_b64 s[26:27], -1
	s_cbranch_vccnz .LBB0_254
	v_lshlrev_b64 v[82:83], 8, v[72:73]
	v_lshl_add_u64 v[82:83], v[82:83], 0, v[64:65]
	s_mov_b64 s[26:27], 0

; DI unsigned pk2(float a, float b) { hwf32x2 f = {a, b}; hwbf16x2 r = __builtin_convertvector(f, hwbf16x2); return __builtin_bit_cast(unsigned, r); }
;   DI void operator()(int mt, int nt, int wm, int wn, int r, int h, f32x16 (&acc)[WM][2]) const {
;     ...
;         for (int j = 0; j < 8; ++j) {
;           const int id = tid + 256 * j;
;           const int c = id & 127, rg = id >> 7;
;           const int lr0 = rg * 8;
;           const int row = mt * (WM * 64) + (lr0 >> 6) * (WM * 32) + ps * 64 + (lr0 & 63);
;           const int b = row / NTOK, t = row % NTOK;
;           const int col = nt * 128 + c;
;           const float bb = bias[col];
;           float x[8];
; #pragma unroll
;           for (int k = 0; k < 8; ++k) x[k] = T[(lr0 + k) * LD + c] + bb;
;           bf16_t* vt = (nt == 17) ? VTC + ((size_t)b * 128 + (col - C_V)) * NTOK : VTA + ((size_t)b * 256 + (col - A_V)) * NTOK;
;           *(uint4*)(vt + t) = make_uint4(pk2(x[0], x[1]), pk2(x[2], x[3]), pk2(x[4], x[5]), pk2(x[6], x[7]));
;         }
.LBB0_256:
	s_add_u32 s26, s68, s26
	s_waitcnt lgkmcnt(0)
	v_mov_b32_e32 v70, v244
	v_pk_add_f32 v[74:75], v[70:71], v[74:75] op_sel_hi:[0,1]
	v_pk_add_f32 v[76:77], v[70:71], v[76:77] op_sel_hi:[0,1]
	v_pk_add_f32 v[78:79], v[70:71], v[78:79] op_sel_hi:[0,1]
	v_pk_add_f32 v[80:81], v[70:71], v[80:81] op_sel_hi:[0,1]
	v_mul_i32_i24_e32 v70, 0x900, v72
	s_addc_u32 s27, s69, s27
	v_sub_u32_e32 v86, v71, v70
	v_mov_b64_e32 v[70:71], s[26:27]
	v_mad_u64_u32 v[90:91], s[26:27], v82, s67, v[70:71]
	v_mov_b32_e32 v70, v91
	v_mad_u64_u32 v[70:71], s[26:27], v83, s67, v[70:71]
	v_mov_b32_e32 v91, v70
	v_ashrrev_i32_e32 v87, 31, v86
	v_cvt_pk_bf16_f32 v70, v74, v75
	v_cvt_pk_bf16_f32 v71, v76, v77
	v_cvt_pk_bf16_f32 v72, v78, v79
	v_cvt_pk_bf16_f32 v73, v80, v81
	v_lshl_add_u64 v[74:75], v[86:87], 1, v[90:91]
	global_store_dwordx4 v[74:75], v[70:73], off
	s_nop 0
	s_and_b64 vcc, exec, s[8:9]
	v_and_b32_e32 v72, 0xffffff8, v96
	v_and_or_b32 v71, v96, 56, v207
	v_mad_u64_u32 v[78:79], s[26:27], v72, s66, v[66:67]
	v_mul_hi_i32 v73, v71, s55
	v_add_u32_e32 v74, 0x400, v78
	v_add_u32_e32 v76, 0x800, v78
	v_or_b32_e32 v79, 7, v96
	v_lshrrev_b32_e32 v82, 31, v73
	v_ashrrev_i32_e32 v83, 9, v73
	ds_read2_b32 v[72:73], v78 offset1:132
	ds_read2_b32 v[74:75], v74 offset0:8 offset1:140
	ds_read2_b32 v[76:77], v76 offset0:16 offset1:148
	v_mad_u64_u32 v[80:81], s[26:27], v79, s66, v[66:67]
	ds_read_b32 v78, v78 offset:3168
	ds_read_b32 v79, v80
	v_add_u32_e32 v82, v83, v82
	v_ashrrev_i32_e32 v83, 31, v82
	s_mov_b64 s[26:27], -1
	s_cbranch_vccnz .LBB0_258
	v_lshlrev_b64 v[80:81], 8, v[82:83]
	v_lshl_add_u64 v[80:81], v[80:81], 0, v[64:65]
	s_mov_b64 s[26:27], 0

; DI unsigned pk2(float a, float b) { hwf32x2 f = {a, b}; hwbf16x2 r = __builtin_convertvector(f, hwbf16x2); return __builtin_bit_cast(unsigned, r); }
;   DI void operator()(int mt, int nt, int wm, int wn, int r, int h, f32x16 (&acc)[WM][2]) const {
;     ...
;         for (int j = 0; j < 8; ++j) {
;           const int id = tid + 256 * j;
;           const int c = id & 127, rg = id >> 7;
;           const int lr0 = rg * 8;
;           const int row = mt * (WM * 64) + (lr0 >> 6) * (WM * 32) + ps * 64 + (lr0 & 63);
;           const int b = row / NTOK, t = row % NTOK;
;           const int col = nt * 128 + c;
;           const float bb = bias[col];
;           float x[8];
; #pragma unroll
;           for (int k = 0; k < 8; ++k) x[k] = T[(lr0 + k) * LD + c] + bb;
;           bf16_t* vt = (nt == 17) ? VTC + ((size_t)b * 128 + (col - C_V)) * NTOK : VTA + ((size_t)b * 256 + (col - A_V)) * NTOK;
;           *(uint4*)(vt + t) = make_uint4(pk2(x[0], x[1]), pk2(x[2], x[3]), pk2(x[4], x[5]), pk2(x[6], x[7]));
;         }
.LBB0_260:
	s_add_u32 s26, s68, s26
	s_waitcnt lgkmcnt(0)
	v_mov_b32_e32 v70, v244
	v_pk_add_f32 v[72:73], v[70:71], v[72:73] op_sel_hi:[0,1]
	v_pk_add_f32 v[74:75], v[70:71], v[74:75] op_sel_hi:[0,1]
	v_pk_add_f32 v[76:77], v[70:71], v[76:77] op_sel_hi:[0,1]
	v_pk_add_f32 v[78:79], v[70:71], v[78:79] op_sel_hi:[0,1]
	v_mul_i32_i24_e32 v70, 0x900, v82
	s_addc_u32 s27, s69, s27
	v_sub_u32_e32 v82, v71, v70
	v_mov_b64_e32 v[70:71], s[26:27]
	v_mad_u64_u32 v[86:87], s[26:27], v80, s67, v[70:71]
	v_mov_b32_e32 v70, v87
	v_mad_u64_u32 v[70:71], s[26:27], v81, s67, v[70:71]
	v_mov_b32_e32 v87, v70
	v_ashrrev_i32_e32 v83, 31, v82
	v_cvt_pk_bf16_f32 v70, v72, v73
	v_cvt_pk_bf16_f32 v71, v74, v75
	v_cvt_pk_bf16_f32 v72, v76, v77
	v_cvt_pk_bf16_f32 v73, v78, v79
	v_lshl_add_u64 v[74:75], v[82:83], 1, v[86:87]
	global_store_dwordx4 v[74:75], v[70:73], off
	s_nop 0
	s_and_b64 vcc, exec, s[8:9]
	v_and_b32_e32 v72, 0xffffff8, v97
	v_and_or_b32 v71, v97, 56, v208
	v_mad_u64_u32 v[78:79], s[26:27], v72, s66, v[66:67]
	v_mul_hi_i32 v73, v71, s55
	v_add_u32_e32 v74, 0x400, v78
	v_add_u32_e32 v76, 0x800, v78
	v_or_b32_e32 v79, 7, v97
	v_lshrrev_b32_e32 v82, 31, v73
	v_ashrrev_i32_e32 v83, 9, v73
	ds_read2_b32 v[72:73], v78 offset1:132
	ds_read2_b32 v[74:75], v74 offset0:8 offset1:140
	ds_read2_b32 v[76:77], v76 offset0:16 offset1:148
	v_mad_u64_u32 v[80:81], s[26:27], v79, s66, v[66:67]
	ds_read_b32 v78, v78 offset:3168
	ds_read_b32 v79, v80
	v_add_u32_e32 v82, v83, v82
	v_ashrrev_i32_e32 v83, 31, v82
	s_mov_b64 s[26:27], -1
	s_cbranch_vccnz .LBB0_262
	v_lshlrev_b64 v[80:81], 8, v[82:83]
	v_lshl_add_u64 v[80:81], v[80:81], 0, v[64:65]
	s_mov_b64 s[26:27], 0

; DI unsigned pk2(float a, float b) { hwf32x2 f = {a, b}; hwbf16x2 r = __builtin_convertvector(f, hwbf16x2); return __builtin_bit_cast(unsigned, r); }
;   DI void operator()(int mt, int nt, int wm, int wn, int r, int h, f32x16 (&acc)[WM][2]) const {
;     ...
;         for (int j = 0; j < 8; ++j) {
;           const int id = tid + 256 * j;
;           const int c = id & 127, rg = id >> 7;
;           const int lr0 = rg * 8;
;           const int row = mt * (WM * 64) + (lr0 >> 6) * (WM * 32) + ps * 64 + (lr0 & 63);
;           const int b = row / NTOK, t = row % NTOK;
;           const int col = nt * 128 + c;
;           const float bb = bias[col];
;           float x[8];
; #pragma unroll
;           for (int k = 0; k < 8; ++k) x[k] = T[(lr0 + k) * LD + c] + bb;
;           bf16_t* vt = (nt == 17) ? VTC + ((size_t)b * 128 + (col - C_V)) * NTOK : VTA + ((size_t)b * 256 + (col - A_V)) * NTOK;
;           *(uint4*)(vt + t) = make_uint4(pk2(x[0], x[1]), pk2(x[2], x[3]), pk2(x[4], x[5]), pk2(x[6], x[7]));
;         }
.LBB0_264:
	s_add_u32 s26, s68, s26
	s_waitcnt lgkmcnt(0)
	v_mov_b32_e32 v70, v244
	v_pk_add_f32 v[72:73], v[70:71], v[72:73] op_sel_hi:[0,1]
	v_pk_add_f32 v[74:75], v[70:71], v[74:75] op_sel_hi:[0,1]
	v_pk_add_f32 v[76:77], v[70:71], v[76:77] op_sel_hi:[0,1]
	v_pk_add_f32 v[78:79], v[70:71], v[78:79] op_sel_hi:[0,1]
	v_mul_i32_i24_e32 v70, 0x900, v82
	s_addc_u32 s27, s69, s27
	v_sub_u32_e32 v82, v71, v70
	v_mov_b64_e32 v[70:71], s[26:27]
	v_mad_u64_u32 v[86:87], s[26:27], v80, s67, v[70:71]
	v_mov_b32_e32 v70, v87
	v_mad_u64_u32 v[70:71], s[26:27], v81, s67, v[70:71]
	v_mov_b32_e32 v87, v70
	v_ashrrev_i32_e32 v83, 31, v82
	v_cvt_pk_bf16_f32 v70, v72, v73
	v_cvt_pk_bf16_f32 v71, v74, v75
	v_cvt_pk_bf16_f32 v72, v76, v77
	v_cvt_pk_bf16_f32 v73, v78, v79
	v_lshl_add_u64 v[74:75], v[82:83], 1, v[86:87]
	global_store_dwordx4 v[74:75], v[70:73], off
	s_nop 0
	s_and_b64 vcc, exec, s[8:9]
	v_and_b32_e32 v72, 0xffffff8, v98
	v_and_or_b32 v71, v98, 56, v209
	v_mad_u64_u32 v[78:79], s[26:27], v72, s66, v[66:67]
	v_mul_hi_i32 v73, v71, s55
	v_add_u32_e32 v74, 0x400, v78
	v_add_u32_e32 v76, 0x800, v78
	v_or_b32_e32 v79, 7, v98
	v_lshrrev_b32_e32 v82, 31, v73
	v_ashrrev_i32_e32 v83, 9, v73
	ds_read2_b32 v[72:73], v78 offset1:132
	ds_read2_b32 v[74:75], v74 offset0:8 offset1:140
	ds_read2_b32 v[76:77], v76 offset0:16 offset1:148
	v_mad_u64_u32 v[80:81], s[26:27], v79, s66, v[66:67]
	ds_read_b32 v78, v78 offset:3168
	ds_read_b32 v79, v80
	v_add_u32_e32 v82, v83, v82
	v_ashrrev_i32_e32 v83, 31, v82
	s_mov_b64 s[26:27], -1
	s_cbranch_vccnz .LBB0_266
	v_lshlrev_b64 v[80:81], 8, v[82:83]
	v_lshl_add_u64 v[80:81], v[80:81], 0, v[64:65]
	s_mov_b64 s[26:27], 0

; DI unsigned pk2(float a, float b) { hwf32x2 f = {a, b}; hwbf16x2 r = __builtin_convertvector(f, hwbf16x2); return __builtin_bit_cast(unsigned, r); }
;   DI void operator()(int mt, int nt, int wm, int wn, int r, int h, f32x16 (&acc)[WM][2]) const {
;     ...
;         for (int j = 0; j < 8; ++j) {
;           const int id = tid + 256 * j;
;           const int c = id & 127, rg = id >> 7;
;           const int lr0 = rg * 8;
;           const int row = mt * (WM * 64) + (lr0 >> 6) * (WM * 32) + ps * 64 + (lr0 & 63);
;           const int b = row / NTOK, t = row % NTOK;
;           const int col = nt * 128 + c;
;           const float bb = bias[col];
;           float x[8];
; #pragma unroll
;           for (int k = 0; k < 8; ++k) x[k] = T[(lr0 + k) * LD + c] + bb;
;           bf16_t* vt = (nt == 17) ? VTC + ((size_t)b * 128 + (col - C_V)) * NTOK : VTA + ((size_t)b * 256 + (col - A_V)) * NTOK;
;           *(uint4*)(vt + t) = make_uint4(pk2(x[0], x[1]), pk2(x[2], x[3]), pk2(x[4], x[5]), pk2(x[6], x[7]));
;         }
.LBB0_268:
	s_add_u32 s26, s68, s26
	s_waitcnt lgkmcnt(0)
	v_mov_b32_e32 v70, v244
	v_pk_add_f32 v[72:73], v[70:71], v[72:73] op_sel_hi:[0,1]
	v_pk_add_f32 v[74:75], v[70:71], v[74:75] op_sel_hi:[0,1]
	v_pk_add_f32 v[76:77], v[70:71], v[76:77] op_sel_hi:[0,1]
	v_pk_add_f32 v[78:79], v[70:71], v[78:79] op_sel_hi:[0,1]
	v_mul_i32_i24_e32 v70, 0x900, v82
	s_addc_u32 s27, s69, s27
	v_sub_u32_e32 v82, v71, v70
	v_mov_b64_e32 v[70:71], s[26:27]
	v_mad_u64_u32 v[86:87], s[26:27], v80, s67, v[70:71]
	v_mov_b32_e32 v70, v87
	v_mad_u64_u32 v[70:71], s[26:27], v81, s67, v[70:71]
	v_mov_b32_e32 v87, v70
	v_ashrrev_i32_e32 v83, 31, v82
	v_cvt_pk_bf16_f32 v70, v72, v73
	v_cvt_pk_bf16_f32 v71, v74, v75
	v_cvt_pk_bf16_f32 v72, v76, v77
	v_cvt_pk_bf16_f32 v73, v78, v79
	v_lshl_add_u64 v[74:75], v[82:83], 1, v[86:87]
	global_store_dwordx4 v[74:75], v[70:73], off
	s_nop 0
	s_and_b64 vcc, exec, s[8:9]
	v_and_b32_e32 v72, 0xffffff8, v99
	v_and_or_b32 v71, v99, 56, v210
	v_mad_u64_u32 v[78:79], s[26:27], v72, s66, v[66:67]
	v_mul_hi_i32 v73, v71, s55
	v_add_u32_e32 v74, 0x400, v78
	v_add_u32_e32 v76, 0x800, v78
	v_or_b32_e32 v79, 7, v99
	v_lshrrev_b32_e32 v82, 31, v73
	v_ashrrev_i32_e32 v83, 9, v73
	ds_read2_b32 v[72:73], v78 offset1:132
	ds_read2_b32 v[74:75], v74 offset0:8 offset1:140
	ds_read2_b32 v[76:77], v76 offset0:16 offset1:148
	v_mad_u64_u32 v[80:81], s[26:27], v79, s66, v[66:67]
	ds_read_b32 v78, v78 offset:3168
	ds_read_b32 v79, v80
	v_add_u32_e32 v82, v83, v82
	v_ashrrev_i32_e32 v83, 31, v82
	s_mov_b64 s[26:27], -1
	s_cbranch_vccnz .LBB0_270
	v_lshlrev_b64 v[80:81], 8, v[82:83]
	v_lshl_add_u64 v[80:81], v[80:81], 0, v[64:65]
	s_mov_b64 s[26:27], 0

; DI unsigned pk2(float a, float b) { hwf32x2 f = {a, b}; hwbf16x2 r = __builtin_convertvector(f, hwbf16x2); return __builtin_bit_cast(unsigned, r); }
;   DI void operator()(int mt, int nt, int wm, int wn, int r, int h, f32x16 (&acc)[WM][2]) const {
;     ...
;         for (int j = 0; j < 8; ++j) {
;           const int id = tid + 256 * j;
;           const int c = id & 127, rg = id >> 7;
;           const int lr0 = rg * 8;
;           const int row = mt * (WM * 64) + (lr0 >> 6) * (WM * 32) + ps * 64 + (lr0 & 63);
;           const int b = row / NTOK, t = row % NTOK;
;           const int col = nt * 128 + c;
;           const float bb = bias[col];
;           float x[8];
; #pragma unroll
;           for (int k = 0; k < 8; ++k) x[k] = T[(lr0 + k) * LD + c] + bb;
;           bf16_t* vt = (nt == 17) ? VTC + ((size_t)b * 128 + (col - C_V)) * NTOK : VTA + ((size_t)b * 256 + (col - A_V)) * NTOK;
;           *(uint4*)(vt + t) = make_uint4(pk2(x[0], x[1]), pk2(x[2], x[3]), pk2(x[4], x[5]), pk2(x[6], x[7]));
.LBB0_272:
	s_add_u32 s26, s68, s26
	s_waitcnt lgkmcnt(0)
	v_mov_b32_e32 v70, v244
	v_pk_add_f32 v[72:73], v[70:71], v[72:73] op_sel_hi:[0,1]
	v_pk_add_f32 v[74:75], v[70:71], v[74:75] op_sel_hi:[0,1]
	v_pk_add_f32 v[76:77], v[70:71], v[76:77] op_sel_hi:[0,1]
	v_pk_add_f32 v[78:79], v[70:71], v[78:79] op_sel_hi:[0,1]
	v_mul_i32_i24_e32 v70, 0x900, v82
	s_addc_u32 s27, s69, s27
	v_sub_u32_e32 v82, v71, v70
	v_mov_b64_e32 v[70:71], s[26:27]
	v_mad_u64_u32 v[86:87], s[26:27], v80, s67, v[70:71]
	v_mov_b32_e32 v70, v87
	v_mad_u64_u32 v[70:71], s[26:27], v81, s67, v[70:71]
	v_mov_b32_e32 v87, v70
	v_ashrrev_i32_e32 v83, 31, v82
	v_cvt_pk_bf16_f32 v70, v72, v73
	v_cvt_pk_bf16_f32 v71, v74, v75
	v_cvt_pk_bf16_f32 v72, v76, v77
	v_cvt_pk_bf16_f32 v73, v78, v79
	v_lshl_add_u64 v[74:75], v[82:83], 1, v[86:87]
	global_store_dwordx4 v[74:75], v[70:73], off
	s_nop 0
	s_and_b64 vcc, exec, s[8:9]
	v_and_b32_e32 v72, 0xffffff8, v100
	v_and_or_b32 v71, v100, 56, v211
	v_mad_u64_u32 v[78:79], s[26:27], v72, s66, v[66:67]
	v_mul_hi_i32 v73, v71, s55
	v_add_u32_e32 v74, 0x400, v78
	v_add_u32_e32 v76, 0x800, v78
	v_or_b32_e32 v79, 7, v100
	v_lshrrev_b32_e32 v82, 31, v73
	v_ashrrev_i32_e32 v83, 9, v73
	ds_read2_b32 v[72:73], v78 offset1:132
	ds_read2_b32 v[74:75], v74 offset0:8 offset1:140
	ds_read2_b32 v[76:77], v76 offset0:16 offset1:148
	v_mad_u64_u32 v[80:81], s[26:27], v79, s66, v[66:67]
	ds_read_b32 v78, v78 offset:3168
	ds_read_b32 v79, v80
	v_add_u32_e32 v82, v83, v82
	v_ashrrev_i32_e32 v83, 31, v82
	s_mov_b64 s[26:27], -1
	s_cbranch_vccnz .LBB0_274
	v_lshlrev_b64 v[80:81], 8, v[82:83]
	v_lshl_add_u64 v[80:81], v[80:81], 0, v[64:65]
	s_mov_b64 s[26:27], 0

; DI unsigned pk2(float a, float b) { hwf32x2 f = {a, b}; hwbf16x2 r = __builtin_convertvector(f, hwbf16x2); return __builtin_bit_cast(unsigned, r); }
;   DI void operator()(int mt, int nt, int wm, int wn, int r, int h, f32x16 (&acc)[WM][2]) const {
;     ...
;         for (int j = 0; j < 8; ++j) {
;           const int id = tid + 256 * j;
;           const int c = id & 127, rg = id >> 7;
;           const int lr0 = rg * 8;
;           const int row = mt * (WM * 64) + (lr0 >> 6) * (WM * 32) + ps * 64 + (lr0 & 63);
;           const int b = row / NTOK, t = row % NTOK;
;           const int col = nt * 128 + c;
;           const float bb = bias[col];
;           float x[8];
; #pragma unroll
;           for (int k = 0; k < 8; ++k) x[k] = T[(lr0 + k) * LD + c] + bb;
;           bf16_t* vt = (nt == 17) ? VTC + ((size_t)b * 128 + (col - C_V)) * NTOK : VTA + ((size_t)b * 256 + (col - A_V)) * NTOK;
;           *(uint4*)(vt + t) = make_uint4(pk2(x[0], x[1]), pk2(x[2], x[3]), pk2(x[4], x[5]), pk2(x[6], x[7]));
.LBB0_276:
	s_add_u32 s26, s68, s26
	s_waitcnt lgkmcnt(0)
	v_mov_b32_e32 v70, v244
	v_pk_add_f32 v[72:73], v[70:71], v[72:73] op_sel_hi:[0,1]
	v_pk_add_f32 v[74:75], v[70:71], v[74:75] op_sel_hi:[0,1]
	v_pk_add_f32 v[76:77], v[70:71], v[76:77] op_sel_hi:[0,1]
	v_pk_add_f32 v[78:79], v[70:71], v[78:79] op_sel_hi:[0,1]
	v_mul_i32_i24_e32 v70, 0x900, v82
	s_addc_u32 s27, s69, s27
	v_sub_u32_e32 v82, v71, v70
	v_mov_b64_e32 v[70:71], s[26:27]
	v_mad_u64_u32 v[86:87], s[26:27], v80, s67, v[70:71]
	v_mov_b32_e32 v70, v87
	v_mad_u64_u32 v[70:71], s[26:27], v81, s67, v[70:71]
	v_mov_b32_e32 v87, v70
	v_ashrrev_i32_e32 v83, 31, v82
	v_cvt_pk_bf16_f32 v70, v72, v73
	v_cvt_pk_bf16_f32 v71, v74, v75
	v_cvt_pk_bf16_f32 v72, v76, v77
	v_cvt_pk_bf16_f32 v73, v78, v79
	v_lshl_add_u64 v[74:75], v[82:83], 1, v[86:87]
	global_store_dwordx4 v[74:75], v[70:73], off
	s_nop 0
	s_and_b64 vcc, exec, s[8:9]
	v_and_b32_e32 v72, 0xffffff8, v101
	v_and_or_b32 v71, v101, 56, v212
	v_mad_u64_u32 v[78:79], s[26:27], v72, s66, v[66:67]
	v_mul_hi_i32 v73, v71, s55
	v_add_u32_e32 v74, 0x400, v78
	v_add_u32_e32 v76, 0x800, v78
	v_or_b32_e32 v79, 7, v101
	v_lshrrev_b32_e32 v82, 31, v73
	v_ashrrev_i32_e32 v83, 9, v73
	ds_read2_b32 v[72:73], v78 offset1:132
	ds_read2_b32 v[74:75], v74 offset0:8 offset1:140
	ds_read2_b32 v[76:77], v76 offset0:16 offset1:148
	v_mad_u64_u32 v[80:81], s[26:27], v79, s66, v[66:67]
	ds_read_b32 v78, v78 offset:3168
	ds_read_b32 v79, v80
	v_add_u32_e32 v82, v83, v82
	v_ashrrev_i32_e32 v83, 31, v82
	s_mov_b64 s[8:9], -1
	s_cbranch_vccnz .LBB0_278
	v_lshlrev_b64 v[80:81], 8, v[82:83]
	v_lshl_add_u64 v[80:81], v[80:81], 0, v[64:65]
	s_mov_b64 s[8:9], 0

; DI unsigned pk2(float a, float b) { hwf32x2 f = {a, b}; hwbf16x2 r = __builtin_convertvector(f, hwbf16x2); return __builtin_bit_cast(unsigned, r); }
;   DI void operator()(int mt, int nt, int wm, int wn, int r, int h, f32x16 (&acc)[WM][2]) const {
;     ...
;         for (int j = 0; j < 8; ++j) {
;           const int id = tid + 256 * j;
;           const int c = id & 127, rg = id >> 7;
;           const int lr0 = rg * 8;
;           const int row = mt * (WM * 64) + (lr0 >> 6) * (WM * 32) + ps * 64 + (lr0 & 63);
;           const int b = row / NTOK, t = row % NTOK;
;           const int col = nt * 128 + c;
;           const float bb = bias[col];
;           float x[8];
; #pragma unroll
;           for (int k = 0; k < 8; ++k) x[k] = T[(lr0 + k) * LD + c] + bb;
;           bf16_t* vt = (nt == 17) ? VTC + ((size_t)b * 128 + (col - C_V)) * NTOK : VTA + ((size_t)b * 256 + (col - A_V)) * NTOK;
;           *(uint4*)(vt + t) = make_uint4(pk2(x[0], x[1]), pk2(x[2], x[3]), pk2(x[4], x[5]), pk2(x[6], x[7]));
.LBB0_280:
	s_add_u32 s8, s68, s8
	s_waitcnt lgkmcnt(0)
	v_mov_b32_e32 v70, v244
	v_pk_add_f32 v[72:73], v[70:71], v[72:73] op_sel_hi:[0,1]
	v_pk_add_f32 v[74:75], v[70:71], v[74:75] op_sel_hi:[0,1]
	v_pk_add_f32 v[76:77], v[70:71], v[76:77] op_sel_hi:[0,1]
	v_pk_add_f32 v[78:79], v[70:71], v[78:79] op_sel_hi:[0,1]
	v_mul_i32_i24_e32 v70, 0x900, v82
	s_addc_u32 s9, s69, s9
	v_sub_u32_e32 v82, v71, v70
	v_mov_b64_e32 v[70:71], s[8:9]
	v_mad_u64_u32 v[86:87], s[8:9], v80, s67, v[70:71]
	v_mov_b32_e32 v70, v87
	v_mad_u64_u32 v[70:71], s[8:9], v81, s67, v[70:71]
	v_mov_b32_e32 v87, v70
	v_ashrrev_i32_e32 v83, 31, v82
	v_cvt_pk_bf16_f32 v70, v72, v73
	v_cvt_pk_bf16_f32 v71, v74, v75
	v_cvt_pk_bf16_f32 v72, v76, v77
	v_cvt_pk_bf16_f32 v73, v78, v79
	v_lshl_add_u64 v[74:75], v[82:83], 1, v[86:87]
	global_store_dwordx4 v[74:75], v[70:73], off

;   DI void operator()(int mt, int nt, int wm, int wn, int r, int h, f32x16 (&acc)[WM][2]) const {
;     ...
;             const float4 p0 = *(const float4*)(T + lr * LD + pc * 8), p1 = *(const float4*)(T + lr * LD + pc * 8 + 4);
;             const float4 c0 = *(const float4*)(bias + nt * 128 + pc * 8), c1 = *(const float4*)(bias + nt * 128 + pc * 8 + 4);
;             const float pr[8] = {p0.x + c0.x, p0.y + c0.y, p0.z + c0.z, p0.w + c0.w, p1.x + c1.x, p1.y + c1.y, p1.z + c1.z, p1.w + c1.w};
;             const int tok = t - NCTX;
;             const int q = (ropemode == 1) ? (cc & 3) : ((cc & 7) >> 1);
;             const int pos = (q < 2) ? (tok >> 6) : (tok & 63);
;             const float2* tab = (ropemode == 1) ? (T32 + pos * 8) : (T64 + pos * 16 + (cc & 1) * 8);
;             const float sgn = (q & 1) ? 1.f : -1.f;
; #pragma unroll
;             for (int k = 0; k < 8; ++k) { const float2 cs = tab[k]; v[k] = v[k] * cs.x + sgn * pr[k] * cs.y; }
.LBB0_287:
	global_load_dwordx4 v[228:231], v[26:27], off
	global_load_dwordx4 v[232:235], v[26:27], off offset:16
	global_load_dwordx4 v[236:239], v[26:27], off offset:32
	global_load_dwordx4 v[240:243], v[26:27], off offset:48
	s_waitcnt vmcnt(0) lgkmcnt(1)
	v_add_f32_e32 v16, v20, v16
	v_add_f32_e32 v17, v21, v17
	v_add_f32_e32 v20, v22, v18
	v_add_f32_e32 v21, v23, v19
	s_waitcnt lgkmcnt(0)
	v_add_f32_e32 v22, v12, v8
	v_add_f32_e32 v23, v13, v9
	v_add_f32_e32 v25, v14, v10
	v_add_f32_e32 v29, v15, v11
	v_mov_b32_e32 v8, v228
	v_mov_b32_e32 v9, v229
	v_mov_b32_e32 v10, v230
	v_mov_b32_e32 v11, v231
	v_mov_b32_e32 v15, v5
	v_cndmask_b32_e64 v14, v16, -v16, s[0:1]
	v_cndmask_b32_e64 v20, v20, -v20, s[0:1]
	v_cndmask_b32_e64 v22, v22, -v22, s[0:1]
	s_waitcnt vmcnt(0) lgkmcnt(0)
	v_mov_b32_e32 v12, v9
	v_cndmask_b32_e64 v9, v17, -v17, s[0:1]
	v_mov_b32_e32 v5, v9
	v_mov_b32_e32 v9, v11
	v_mov_b32_e32 v13, v10
	v_pk_mul_f32 v[16:17], v[4:5], v[8:9]
	v_mov_b32_e32 v8, v232
	v_mov_b32_e32 v9, v233
	v_mov_b32_e32 v10, v234
	v_mov_b32_e32 v11, v235
	v_cndmask_b32_e64 v4, v21, -v21, s[0:1]
	v_mov_b32_e32 v21, v7
	v_mov_b32_e32 v7, v4
	s_waitcnt vmcnt(0) lgkmcnt(0)
	v_mov_b32_e32 v18, v9
	v_mov_b32_e32 v9, v11
	v_pk_mul_f32 v[8:9], v[6:7], v[8:9]
	v_mov_b32_e32 v4, v236
	v_mov_b32_e32 v5, v237
	v_mov_b32_e32 v6, v238
	v_mov_b32_e32 v7, v239
	v_mov_b32_e32 v19, v10
	s_waitcnt vmcnt(0) lgkmcnt(0)
	v_mov_b32_e32 v10, v5
	v_cndmask_b32_e64 v5, v23, -v23, s[0:1]
	v_mov_b32_e32 v23, v1
	v_mov_b32_e32 v1, v5
	v_mov_b32_e32 v5, v7
	v_mov_b32_e32 v11, v6
	v_pk_mul_f32 v[0:1], v[0:1], v[4:5]
	v_mov_b32_e32 v4, v240
	v_mov_b32_e32 v5, v241
	v_mov_b32_e32 v6, v242
	v_mov_b32_e32 v7, v243
	v_pk_fma_f32 v[0:1], v[22:23], v[10:11], v[0:1]
	s_waitcnt vmcnt(0) lgkmcnt(0)
	v_mul_f32_e32 v2, v2, v4
	v_cndmask_b32_e64 v4, v25, -v25, s[0:1]
	v_mul_f32_e32 v26, v4, v5
	v_cndmask_b32_e64 v5, v29, -v29, s[0:1]
	v_mov_b32_e32 v4, v3
	v_pk_mul_f32 v[4:5], v[4:5], v[6:7]
	v_pk_fma_f32 v[6:7], v[20:21], v[18:19], v[8:9]
	v_mov_b32_e32 v3, v4
	v_mov_b32_e32 v27, v5
	v_pk_fma_f32 v[4:5], v[14:15], v[12:13], v[16:17]
	v_pk_add_f32 v[2:3], v[2:3], v[26:27]

;   DI void operator()(int mt, int nt, int wm, int wn, int r, int h, f32x16 (&acc)[WM][2]) const {
;     ...
;             const float4 p0 = *(const float4*)(T + lr * LD + pc * 8), p1 = *(const float4*)(T + lr * LD + pc * 8 + 4);
;             const float4 c0 = *(const float4*)(bias + nt * 128 + pc * 8), c1 = *(const float4*)(bias + nt * 128 + pc * 8 + 4);
;             const float pr[8] = {p0.x + c0.x, p0.y + c0.y, p0.z + c0.z, p0.w + c0.w, p1.x + c1.x, p1.y + c1.y, p1.z + c1.z, p1.w + c1.w};
;             const int tok = t - NCTX;
;             const int q = (ropemode == 1) ? (cc & 3) : ((cc & 7) >> 1);
;             const int pos = (q < 2) ? (tok >> 6) : (tok & 63);
;             const float2* tab = (ropemode == 1) ? (T32 + pos * 8) : (T64 + pos * 16 + (cc & 1) * 8);
;             const float sgn = (q & 1) ? 1.f : -1.f;
; #pragma unroll
;             for (int k = 0; k < 8; ++k) { const float2 cs = tab[k]; v[k] = v[k] * cs.x + sgn * pr[k] * cs.y; }
.LBB0_296:
	global_load_dwordx4 v[228:231], v[26:27], off
	global_load_dwordx4 v[232:235], v[26:27], off offset:16
	global_load_dwordx4 v[236:239], v[26:27], off offset:32
	global_load_dwordx4 v[240:243], v[26:27], off offset:48
	s_waitcnt vmcnt(0) lgkmcnt(1)
	v_add_f32_e32 v16, v20, v16
	v_add_f32_e32 v17, v21, v17
	v_add_f32_e32 v20, v22, v18
	v_add_f32_e32 v21, v23, v19
	s_waitcnt lgkmcnt(0)
	v_add_f32_e32 v22, v12, v8
	v_add_f32_e32 v23, v13, v9
	v_add_f32_e32 v25, v14, v10
	v_add_f32_e32 v30, v15, v11
	v_mov_b32_e32 v8, v228
	v_mov_b32_e32 v9, v229
	v_mov_b32_e32 v10, v230
	v_mov_b32_e32 v11, v231
	v_mov_b32_e32 v15, v5
	v_cndmask_b32_e64 v14, v16, -v16, s[0:1]
	v_cndmask_b32_e64 v20, v20, -v20, s[0:1]
	v_cndmask_b32_e64 v22, v22, -v22, s[0:1]
	s_waitcnt vmcnt(0) lgkmcnt(0)
	v_mov_b32_e32 v12, v9
	v_cndmask_b32_e64 v9, v17, -v17, s[0:1]
	v_mov_b32_e32 v5, v9
	v_mov_b32_e32 v9, v11
	v_mov_b32_e32 v13, v10
	v_pk_mul_f32 v[16:17], v[4:5], v[8:9]
	v_mov_b32_e32 v8, v232
	v_mov_b32_e32 v9, v233
	v_mov_b32_e32 v10, v234
	v_mov_b32_e32 v11, v235
	v_cndmask_b32_e64 v4, v21, -v21, s[0:1]
	v_mov_b32_e32 v21, v7
	v_mov_b32_e32 v7, v4
	s_waitcnt vmcnt(0) lgkmcnt(0)
	v_mov_b32_e32 v18, v9
	v_mov_b32_e32 v9, v11
	v_pk_mul_f32 v[8:9], v[6:7], v[8:9]
	v_mov_b32_e32 v4, v236
	v_mov_b32_e32 v5, v237
	v_mov_b32_e32 v6, v238
	v_mov_b32_e32 v7, v239
	v_mov_b32_e32 v19, v10
	s_waitcnt vmcnt(0) lgkmcnt(0)
	v_mov_b32_e32 v10, v5
	v_cndmask_b32_e64 v5, v23, -v23, s[0:1]
	v_mov_b32_e32 v23, v1
	v_mov_b32_e32 v1, v5
	v_mov_b32_e32 v5, v7
	v_mov_b32_e32 v11, v6
	v_pk_mul_f32 v[0:1], v[0:1], v[4:5]
	v_mov_b32_e32 v4, v240
	v_mov_b32_e32 v5, v241
	v_mov_b32_e32 v6, v242
	v_mov_b32_e32 v7, v243
	v_pk_fma_f32 v[0:1], v[22:23], v[10:11], v[0:1]
	s_waitcnt vmcnt(0) lgkmcnt(0)
	v_mul_f32_e32 v2, v2, v4
	v_cndmask_b32_e64 v4, v25, -v25, s[0:1]
	v_mul_f32_e32 v26, v4, v5
	v_cndmask_b32_e64 v5, v30, -v30, s[0:1]
	v_mov_b32_e32 v4, v3
	v_pk_mul_f32 v[4:5], v[4:5], v[6:7]
	v_pk_fma_f32 v[6:7], v[20:21], v[18:19], v[8:9]
	v_mov_b32_e32 v3, v4
	v_mov_b32_e32 v27, v5
	v_pk_fma_f32 v[4:5], v[14:15], v[12:13], v[16:17]
	v_pk_add_f32 v[2:3], v[2:3], v[26:27]

;   DI void operator()(int mt, int nt, int wm, int wn, int r, int h, f32x16 (&acc)[WM][2]) const {
;     ...
;             const float4 p0 = *(const float4*)(T + lr * LD + pc * 8), p1 = *(const float4*)(T + lr * LD + pc * 8 + 4);
;             const float4 c0 = *(const float4*)(bias + nt * 128 + pc * 8), c1 = *(const float4*)(bias + nt * 128 + pc * 8 + 4);
;             const float pr[8] = {p0.x + c0.x, p0.y + c0.y, p0.z + c0.z, p0.w + c0.w, p1.x + c1.x, p1.y + c1.y, p1.z + c1.z, p1.w + c1.w};
;             const int tok = t - NCTX;
;             const int q = (ropemode == 1) ? (cc & 3) : ((cc & 7) >> 1);
;             const int pos = (q < 2) ? (tok >> 6) : (tok & 63);
;             const float2* tab = (ropemode == 1) ? (T32 + pos * 8) : (T64 + pos * 16 + (cc & 1) * 8);
;             const float sgn = (q & 1) ? 1.f : -1.f;
; #pragma unroll
;             for (int k = 0; k < 8; ++k) { const float2 cs = tab[k]; v[k] = v[k] * cs.x + sgn * pr[k] * cs.y; }
.LBB0_305:
	global_load_dwordx4 v[228:231], v[26:27], off
	global_load_dwordx4 v[232:235], v[26:27], off offset:16
	global_load_dwordx4 v[236:239], v[26:27], off offset:32
	global_load_dwordx4 v[240:243], v[26:27], off offset:48
	s_waitcnt vmcnt(0) lgkmcnt(1)
	v_add_f32_e32 v16, v20, v16
	v_add_f32_e32 v17, v21, v17
	v_add_f32_e32 v20, v22, v18
	v_add_f32_e32 v21, v23, v19
	s_waitcnt lgkmcnt(0)
	v_add_f32_e32 v22, v12, v8
	v_add_f32_e32 v23, v13, v9
	v_add_f32_e32 v25, v14, v10
	v_add_f32_e32 v31, v15, v11
	v_mov_b32_e32 v8, v228
	v_mov_b32_e32 v9, v229
	v_mov_b32_e32 v10, v230
	v_mov_b32_e32 v11, v231
	v_mov_b32_e32 v15, v5
	v_cndmask_b32_e64 v14, v16, -v16, s[0:1]
	v_cndmask_b32_e64 v20, v20, -v20, s[0:1]
	v_cndmask_b32_e64 v22, v22, -v22, s[0:1]
	s_waitcnt vmcnt(0) lgkmcnt(0)
	v_mov_b32_e32 v12, v9
	v_cndmask_b32_e64 v9, v17, -v17, s[0:1]
	v_mov_b32_e32 v5, v9
	v_mov_b32_e32 v9, v11
	v_mov_b32_e32 v13, v10
	v_pk_mul_f32 v[16:17], v[4:5], v[8:9]
	v_mov_b32_e32 v8, v232
	v_mov_b32_e32 v9, v233
	v_mov_b32_e32 v10, v234
	v_mov_b32_e32 v11, v235
	v_cndmask_b32_e64 v4, v21, -v21, s[0:1]
	v_mov_b32_e32 v21, v7
	v_mov_b32_e32 v7, v4
	s_waitcnt vmcnt(0) lgkmcnt(0)
	v_mov_b32_e32 v18, v9
	v_mov_b32_e32 v9, v11
	v_pk_mul_f32 v[8:9], v[6:7], v[8:9]
	v_mov_b32_e32 v4, v236
	v_mov_b32_e32 v5, v237
	v_mov_b32_e32 v6, v238
	v_mov_b32_e32 v7, v239
	v_mov_b32_e32 v19, v10
	s_waitcnt vmcnt(0) lgkmcnt(0)
	v_mov_b32_e32 v10, v5
	v_cndmask_b32_e64 v5, v23, -v23, s[0:1]
	v_mov_b32_e32 v23, v1
	v_mov_b32_e32 v1, v5
	v_mov_b32_e32 v5, v7
	v_mov_b32_e32 v11, v6
	v_pk_mul_f32 v[0:1], v[0:1], v[4:5]
	v_mov_b32_e32 v4, v240
	v_mov_b32_e32 v5, v241
	v_mov_b32_e32 v6, v242
	v_mov_b32_e32 v7, v243
	v_pk_fma_f32 v[0:1], v[22:23], v[10:11], v[0:1]
	s_waitcnt vmcnt(0) lgkmcnt(0)
	v_mul_f32_e32 v2, v2, v4
	v_cndmask_b32_e64 v4, v25, -v25, s[0:1]
	v_mul_f32_e32 v26, v4, v5
	v_cndmask_b32_e64 v5, v31, -v31, s[0:1]
	v_mov_b32_e32 v4, v3
	v_pk_mul_f32 v[4:5], v[4:5], v[6:7]
	v_pk_fma_f32 v[6:7], v[20:21], v[18:19], v[8:9]
	v_mov_b32_e32 v3, v4
	v_mov_b32_e32 v27, v5
	v_pk_fma_f32 v[4:5], v[14:15], v[12:13], v[16:17]
	v_pk_add_f32 v[2:3], v[2:3], v[26:27]

;   DI void operator()(int mt, int nt, int wm, int wn, int r, int h, f32x16 (&acc)[WM][2]) const {
;     ...
;             const float4 p0 = *(const float4*)(T + lr * LD + pc * 8), p1 = *(const float4*)(T + lr * LD + pc * 8 + 4);
;             const float4 c0 = *(const float4*)(bias + nt * 128 + pc * 8), c1 = *(const float4*)(bias + nt * 128 + pc * 8 + 4);
;             const float pr[8] = {p0.x + c0.x, p0.y + c0.y, p0.z + c0.z, p0.w + c0.w, p1.x + c1.x, p1.y + c1.y, p1.z + c1.z, p1.w + c1.w};
;             const int tok = t - NCTX;
;             const int q = (ropemode == 1) ? (cc & 3) : ((cc & 7) >> 1);
;             const int pos = (q < 2) ? (tok >> 6) : (tok & 63);
;             const float2* tab = (ropemode == 1) ? (T32 + pos * 8) : (T64 + pos * 16 + (cc & 1) * 8);
;             const float sgn = (q & 1) ? 1.f : -1.f;
; #pragma unroll
;             for (int k = 0; k < 8; ++k) { const float2 cs = tab[k]; v[k] = v[k] * cs.x + sgn * pr[k] * cs.y; }
.LBB0_314:
	global_load_dwordx4 v[228:231], v[26:27], off
	global_load_dwordx4 v[232:235], v[26:27], off offset:16
	global_load_dwordx4 v[236:239], v[26:27], off offset:32
	global_load_dwordx4 v[240:243], v[26:27], off offset:48
	s_waitcnt vmcnt(0) lgkmcnt(1)
	v_add_f32_e32 v16, v20, v16
	v_add_f32_e32 v17, v21, v17
	v_add_f32_e32 v20, v22, v18
	v_add_f32_e32 v21, v23, v19
	s_waitcnt lgkmcnt(0)
	v_add_f32_e32 v22, v12, v8
	v_add_f32_e32 v23, v13, v9
	v_add_f32_e32 v25, v14, v10
	v_add_f32_e32 v32, v15, v11
	v_mov_b32_e32 v8, v228
	v_mov_b32_e32 v9, v229
	v_mov_b32_e32 v10, v230
	v_mov_b32_e32 v11, v231
	v_mov_b32_e32 v15, v5
	v_cndmask_b32_e64 v14, v16, -v16, s[0:1]
	v_cndmask_b32_e64 v20, v20, -v20, s[0:1]
	v_cndmask_b32_e64 v22, v22, -v22, s[0:1]
	s_waitcnt vmcnt(0) lgkmcnt(0)
	v_mov_b32_e32 v12, v9
	v_cndmask_b32_e64 v9, v17, -v17, s[0:1]
	v_mov_b32_e32 v5, v9
	v_mov_b32_e32 v9, v11
	v_mov_b32_e32 v13, v10
	v_pk_mul_f32 v[16:17], v[4:5], v[8:9]
	v_mov_b32_e32 v8, v232
	v_mov_b32_e32 v9, v233
	v_mov_b32_e32 v10, v234
	v_mov_b32_e32 v11, v235
	v_cndmask_b32_e64 v4, v21, -v21, s[0:1]
	v_mov_b32_e32 v21, v7
	v_mov_b32_e32 v7, v4
	s_waitcnt vmcnt(0) lgkmcnt(0)
	v_mov_b32_e32 v18, v9
	v_mov_b32_e32 v9, v11
	v_pk_mul_f32 v[8:9], v[6:7], v[8:9]
	v_mov_b32_e32 v4, v236
	v_mov_b32_e32 v5, v237
	v_mov_b32_e32 v6, v238
	v_mov_b32_e32 v7, v239
	v_mov_b32_e32 v19, v10
	s_waitcnt vmcnt(0) lgkmcnt(0)
	v_mov_b32_e32 v10, v5
	v_cndmask_b32_e64 v5, v23, -v23, s[0:1]
	v_mov_b32_e32 v23, v1
	v_mov_b32_e32 v1, v5
	v_mov_b32_e32 v5, v7
	v_mov_b32_e32 v11, v6
	v_pk_mul_f32 v[0:1], v[0:1], v[4:5]
	v_mov_b32_e32 v4, v240
	v_mov_b32_e32 v5, v241
	v_mov_b32_e32 v6, v242
	v_mov_b32_e32 v7, v243
	v_pk_fma_f32 v[0:1], v[22:23], v[10:11], v[0:1]
	s_waitcnt vmcnt(0) lgkmcnt(0)
	v_mul_f32_e32 v2, v2, v4
	v_cndmask_b32_e64 v4, v25, -v25, s[0:1]
	v_mul_f32_e32 v26, v4, v5
	v_cndmask_b32_e64 v5, v32, -v32, s[0:1]
	v_mov_b32_e32 v4, v3
	v_pk_mul_f32 v[4:5], v[4:5], v[6:7]
	v_pk_fma_f32 v[6:7], v[20:21], v[18:19], v[8:9]
	v_mov_b32_e32 v3, v4
	v_mov_b32_e32 v27, v5
	v_pk_fma_f32 v[4:5], v[14:15], v[12:13], v[16:17]
	v_pk_add_f32 v[2:3], v[2:3], v[26:27]

;   DI void operator()(int mt, int nt, int wm, int wn, int r, int h, f32x16 (&acc)[WM][2]) const {
;     ...
;             const float4 p0 = *(const float4*)(T + lr * LD + pc * 8), p1 = *(const float4*)(T + lr * LD + pc * 8 + 4);
;             const float4 c0 = *(const float4*)(bias + nt * 128 + pc * 8), c1 = *(const float4*)(bias + nt * 128 + pc * 8 + 4);
;             const float pr[8] = {p0.x + c0.x, p0.y + c0.y, p0.z + c0.z, p0.w + c0.w, p1.x + c1.x, p1.y + c1.y, p1.z + c1.z, p1.w + c1.w};
;             const int tok = t - NCTX;
;             const int q = (ropemode == 1) ? (cc & 3) : ((cc & 7) >> 1);
;             const int pos = (q < 2) ? (tok >> 6) : (tok & 63);
;             const float2* tab = (ropemode == 1) ? (T32 + pos * 8) : (T64 + pos * 16 + (cc & 1) * 8);
;             const float sgn = (q & 1) ? 1.f : -1.f;
; #pragma unroll
;             for (int k = 0; k < 8; ++k) { const float2 cs = tab[k]; v[k] = v[k] * cs.x + sgn * pr[k] * cs.y; }
.LBB0_323:
	global_load_dwordx4 v[228:231], v[26:27], off
	global_load_dwordx4 v[232:235], v[26:27], off offset:16
	global_load_dwordx4 v[236:239], v[26:27], off offset:32
	global_load_dwordx4 v[240:243], v[26:27], off offset:48
	s_waitcnt vmcnt(0) lgkmcnt(1)
	v_add_f32_e32 v16, v20, v16
	v_add_f32_e32 v17, v21, v17
	v_add_f32_e32 v20, v22, v18
	v_add_f32_e32 v21, v23, v19
	s_waitcnt lgkmcnt(0)
	v_add_f32_e32 v22, v12, v8
	v_add_f32_e32 v23, v13, v9
	v_add_f32_e32 v25, v14, v10
	v_add_f32_e32 v33, v15, v11
	v_mov_b32_e32 v8, v228
	v_mov_b32_e32 v9, v229
	v_mov_b32_e32 v10, v230
	v_mov_b32_e32 v11, v231
	v_mov_b32_e32 v15, v5
	v_cndmask_b32_e64 v14, v16, -v16, s[0:1]
	v_cndmask_b32_e64 v20, v20, -v20, s[0:1]
	v_cndmask_b32_e64 v22, v22, -v22, s[0:1]
	s_waitcnt vmcnt(0) lgkmcnt(0)
	v_mov_b32_e32 v12, v9
	v_cndmask_b32_e64 v9, v17, -v17, s[0:1]
	v_mov_b32_e32 v5, v9
	v_mov_b32_e32 v9, v11
	v_mov_b32_e32 v13, v10
	v_pk_mul_f32 v[16:17], v[4:5], v[8:9]
	v_mov_b32_e32 v8, v232
	v_mov_b32_e32 v9, v233
	v_mov_b32_e32 v10, v234
	v_mov_b32_e32 v11, v235
	v_cndmask_b32_e64 v4, v21, -v21, s[0:1]
	v_mov_b32_e32 v21, v7
	v_mov_b32_e32 v7, v4
	s_waitcnt vmcnt(0) lgkmcnt(0)
	v_mov_b32_e32 v18, v9
	v_mov_b32_e32 v9, v11
	v_pk_mul_f32 v[8:9], v[6:7], v[8:9]
	v_mov_b32_e32 v4, v236
	v_mov_b32_e32 v5, v237
	v_mov_b32_e32 v6, v238
	v_mov_b32_e32 v7, v239
	v_mov_b32_e32 v19, v10
	s_waitcnt vmcnt(0) lgkmcnt(0)
	v_mov_b32_e32 v10, v5
	v_cndmask_b32_e64 v5, v23, -v23, s[0:1]
	v_mov_b32_e32 v23, v1
	v_mov_b32_e32 v1, v5
	v_mov_b32_e32 v5, v7
	v_mov_b32_e32 v11, v6
	v_pk_mul_f32 v[0:1], v[0:1], v[4:5]
	v_mov_b32_e32 v4, v240
	v_mov_b32_e32 v5, v241
	v_mov_b32_e32 v6, v242
	v_mov_b32_e32 v7, v243
	v_pk_fma_f32 v[0:1], v[22:23], v[10:11], v[0:1]
	s_waitcnt vmcnt(0) lgkmcnt(0)
	v_mul_f32_e32 v2, v2, v4
	v_cndmask_b32_e64 v4, v25, -v25, s[0:1]
	v_mul_f32_e32 v26, v4, v5
	v_cndmask_b32_e64 v5, v33, -v33, s[0:1]
	v_mov_b32_e32 v4, v3
	v_pk_mul_f32 v[4:5], v[4:5], v[6:7]
	v_pk_fma_f32 v[6:7], v[20:21], v[18:19], v[8:9]
	v_mov_b32_e32 v3, v4
	v_mov_b32_e32 v27, v5
	v_pk_fma_f32 v[4:5], v[14:15], v[12:13], v[16:17]
	v_pk_add_f32 v[2:3], v[2:3], v[26:27]

;   DI void operator()(int mt, int nt, int wm, int wn, int r, int h, f32x16 (&acc)[WM][2]) const {
;     ...
;             const float4 p0 = *(const float4*)(T + lr * LD + pc * 8), p1 = *(const float4*)(T + lr * LD + pc * 8 + 4);
;             const float4 c0 = *(const float4*)(bias + nt * 128 + pc * 8), c1 = *(const float4*)(bias + nt * 128 + pc * 8 + 4);
;             const float pr[8] = {p0.x + c0.x, p0.y + c0.y, p0.z + c0.z, p0.w + c0.w, p1.x + c1.x, p1.y + c1.y, p1.z + c1.z, p1.w + c1.w};
;             const int tok = t - NCTX;
;             const int q = (ropemode == 1) ? (cc & 3) : ((cc & 7) >> 1);
;             const int pos = (q < 2) ? (tok >> 6) : (tok & 63);
;             const float2* tab = (ropemode == 1) ? (T32 + pos * 8) : (T64 + pos * 16 + (cc & 1) * 8);
;             const float sgn = (q & 1) ? 1.f : -1.f;
; #pragma unroll
;             for (int k = 0; k < 8; ++k) { const float2 cs = tab[k]; v[k] = v[k] * cs.x + sgn * pr[k] * cs.y; }
.LBB0_332:
	global_load_dwordx4 v[228:231], v[26:27], off
	global_load_dwordx4 v[232:235], v[26:27], off offset:16
	global_load_dwordx4 v[236:239], v[26:27], off offset:32
	global_load_dwordx4 v[240:243], v[26:27], off offset:48
	s_waitcnt vmcnt(0) lgkmcnt(1)
	v_add_f32_e32 v16, v20, v16
	v_add_f32_e32 v17, v21, v17
	v_add_f32_e32 v20, v22, v18
	v_add_f32_e32 v21, v23, v19
	s_waitcnt lgkmcnt(0)
	v_add_f32_e32 v22, v12, v8
	v_add_f32_e32 v23, v13, v9
	v_add_f32_e32 v25, v14, v10
	v_add_f32_e32 v34, v15, v11
	v_mov_b32_e32 v8, v228
	v_mov_b32_e32 v9, v229
	v_mov_b32_e32 v10, v230
	v_mov_b32_e32 v11, v231
	v_mov_b32_e32 v15, v5
	v_cndmask_b32_e64 v14, v16, -v16, s[0:1]
	v_cndmask_b32_e64 v20, v20, -v20, s[0:1]
	v_cndmask_b32_e64 v22, v22, -v22, s[0:1]
	s_waitcnt vmcnt(0) lgkmcnt(0)
	v_mov_b32_e32 v12, v9
	v_cndmask_b32_e64 v9, v17, -v17, s[0:1]
	v_mov_b32_e32 v5, v9
	v_mov_b32_e32 v9, v11
	v_mov_b32_e32 v13, v10
	v_pk_mul_f32 v[16:17], v[4:5], v[8:9]
	v_mov_b32_e32 v8, v232
	v_mov_b32_e32 v9, v233
	v_mov_b32_e32 v10, v234
	v_mov_b32_e32 v11, v235
	v_cndmask_b32_e64 v4, v21, -v21, s[0:1]
	v_mov_b32_e32 v21, v7
	v_mov_b32_e32 v7, v4
	s_waitcnt vmcnt(0) lgkmcnt(0)
	v_mov_b32_e32 v18, v9
	v_mov_b32_e32 v9, v11
	v_pk_mul_f32 v[8:9], v[6:7], v[8:9]
	v_mov_b32_e32 v4, v236
	v_mov_b32_e32 v5, v237
	v_mov_b32_e32 v6, v238
	v_mov_b32_e32 v7, v239
	v_mov_b32_e32 v19, v10
	s_waitcnt vmcnt(0) lgkmcnt(0)
	v_mov_b32_e32 v10, v5
	v_cndmask_b32_e64 v5, v23, -v23, s[0:1]
	v_mov_b32_e32 v23, v1
	v_mov_b32_e32 v1, v5
	v_mov_b32_e32 v5, v7
	v_mov_b32_e32 v11, v6
	v_pk_mul_f32 v[0:1], v[0:1], v[4:5]
	v_mov_b32_e32 v4, v240
	v_mov_b32_e32 v5, v241
	v_mov_b32_e32 v6, v242
	v_mov_b32_e32 v7, v243
	v_pk_fma_f32 v[0:1], v[22:23], v[10:11], v[0:1]
	s_waitcnt vmcnt(0) lgkmcnt(0)
	v_mul_f32_e32 v2, v2, v4
	v_cndmask_b32_e64 v4, v25, -v25, s[0:1]
	v_mul_f32_e32 v26, v4, v5
	v_cndmask_b32_e64 v5, v34, -v34, s[0:1]
	v_mov_b32_e32 v4, v3
	v_pk_mul_f32 v[4:5], v[4:5], v[6:7]
	v_pk_fma_f32 v[6:7], v[20:21], v[18:19], v[8:9]
	v_mov_b32_e32 v3, v4
	v_mov_b32_e32 v27, v5
	v_pk_fma_f32 v[4:5], v[14:15], v[12:13], v[16:17]
	v_pk_add_f32 v[2:3], v[2:3], v[26:27]

;   DI void operator()(int mt, int nt, int wm, int wn, int r, int h, f32x16 (&acc)[WM][2]) const {
;     ...
;             const float4 p0 = *(const float4*)(T + lr * LD + pc * 8), p1 = *(const float4*)(T + lr * LD + pc * 8 + 4);
;             const float4 c0 = *(const float4*)(bias + nt * 128 + pc * 8), c1 = *(const float4*)(bias + nt * 128 + pc * 8 + 4);
;             const float pr[8] = {p0.x + c0.x, p0.y + c0.y, p0.z + c0.z, p0.w + c0.w, p1.x + c1.x, p1.y + c1.y, p1.z + c1.z, p1.w + c1.w};
;             const int tok = t - NCTX;
;             const int q = (ropemode == 1) ? (cc & 3) : ((cc & 7) >> 1);
;             const int pos = (q < 2) ? (tok >> 6) : (tok & 63);
;             const float2* tab = (ropemode == 1) ? (T32 + pos * 8) : (T64 + pos * 16 + (cc & 1) * 8);
;             const float sgn = (q & 1) ? 1.f : -1.f;
; #pragma unroll
;             for (int k = 0; k < 8; ++k) { const float2 cs = tab[k]; v[k] = v[k] * cs.x + sgn * pr[k] * cs.y; }
.LBB0_341:
	global_load_dwordx4 v[228:231], v[26:27], off
	global_load_dwordx4 v[232:235], v[26:27], off offset:16
	global_load_dwordx4 v[236:239], v[26:27], off offset:32
	global_load_dwordx4 v[240:243], v[26:27], off offset:48
	s_waitcnt vmcnt(0) lgkmcnt(1)
	v_add_f32_e32 v16, v20, v16
	v_add_f32_e32 v17, v21, v17
	v_add_f32_e32 v20, v22, v18
	v_add_f32_e32 v21, v23, v19
	s_waitcnt lgkmcnt(0)
	v_add_f32_e32 v22, v12, v8
	v_add_f32_e32 v23, v13, v9
	v_add_f32_e32 v25, v14, v10
	v_add_f32_e32 v35, v15, v11
	v_mov_b32_e32 v8, v228
	v_mov_b32_e32 v9, v229
	v_mov_b32_e32 v10, v230
	v_mov_b32_e32 v11, v231
	v_mov_b32_e32 v15, v5
	v_cndmask_b32_e64 v14, v16, -v16, s[0:1]
	v_cndmask_b32_e64 v20, v20, -v20, s[0:1]
	v_cndmask_b32_e64 v22, v22, -v22, s[0:1]
	s_waitcnt vmcnt(0) lgkmcnt(0)
	v_mov_b32_e32 v12, v9
	v_cndmask_b32_e64 v9, v17, -v17, s[0:1]
	v_mov_b32_e32 v5, v9
	v_mov_b32_e32 v9, v11
	v_mov_b32_e32 v13, v10
	v_pk_mul_f32 v[16:17], v[4:5], v[8:9]
	v_mov_b32_e32 v8, v232
	v_mov_b32_e32 v9, v233
	v_mov_b32_e32 v10, v234
	v_mov_b32_e32 v11, v235
	v_cndmask_b32_e64 v4, v21, -v21, s[0:1]
	v_mov_b32_e32 v21, v7
	v_mov_b32_e32 v7, v4
	s_waitcnt vmcnt(0) lgkmcnt(0)
	v_mov_b32_e32 v18, v9
	v_mov_b32_e32 v9, v11
	v_pk_mul_f32 v[8:9], v[6:7], v[8:9]
	v_mov_b32_e32 v4, v236
	v_mov_b32_e32 v5, v237
	v_mov_b32_e32 v6, v238
	v_mov_b32_e32 v7, v239
	v_mov_b32_e32 v19, v10
	s_waitcnt vmcnt(0) lgkmcnt(0)
	v_mov_b32_e32 v10, v5
	v_cndmask_b32_e64 v5, v23, -v23, s[0:1]
	v_mov_b32_e32 v23, v1
	v_mov_b32_e32 v1, v5
	v_mov_b32_e32 v5, v7
	v_mov_b32_e32 v11, v6
	v_pk_mul_f32 v[0:1], v[0:1], v[4:5]
	v_mov_b32_e32 v4, v240
	v_mov_b32_e32 v5, v241
	v_mov_b32_e32 v6, v242
	v_mov_b32_e32 v7, v243
	v_pk_fma_f32 v[0:1], v[22:23], v[10:11], v[0:1]
	s_waitcnt vmcnt(0) lgkmcnt(0)
	v_mul_f32_e32 v2, v2, v4
	v_cndmask_b32_e64 v4, v25, -v25, s[0:1]
	v_mul_f32_e32 v26, v4, v5
	v_cndmask_b32_e64 v5, v35, -v35, s[0:1]
	v_mov_b32_e32 v4, v3
	v_pk_mul_f32 v[4:5], v[4:5], v[6:7]
	v_pk_fma_f32 v[6:7], v[20:21], v[18:19], v[8:9]
	v_mov_b32_e32 v3, v4
	v_mov_b32_e32 v27, v5
	v_pk_fma_f32 v[4:5], v[14:15], v[12:13], v[16:17]
	v_pk_add_f32 v[2:3], v[2:3], v[26:27]

;   DI void operator()(int mt, int nt, int wm, int wn, int r, int h, f32x16 (&acc)[WM][2]) const {
;     ...
;             const float4 p0 = *(const float4*)(T + lr * LD + pc * 8), p1 = *(const float4*)(T + lr * LD + pc * 8 + 4);
;             const float4 c0 = *(const float4*)(bias + nt * 128 + pc * 8), c1 = *(const float4*)(bias + nt * 128 + pc * 8 + 4);
;             const float pr[8] = {p0.x + c0.x, p0.y + c0.y, p0.z + c0.z, p0.w + c0.w, p1.x + c1.x, p1.y + c1.y, p1.z + c1.z, p1.w + c1.w};
;             const int tok = t - NCTX;
;             const int q = (ropemode == 1) ? (cc & 3) : ((cc & 7) >> 1);
;             const int pos = (q < 2) ? (tok >> 6) : (tok & 63);
;             const float2* tab = (ropemode == 1) ? (T32 + pos * 8) : (T64 + pos * 16 + (cc & 1) * 8);
;             const float sgn = (q & 1) ? 1.f : -1.f;
; #pragma unroll
;             for (int k = 0; k < 8; ++k) { const float2 cs = tab[k]; v[k] = v[k] * cs.x + sgn * pr[k] * cs.y; }
.LBB0_350:
	global_load_dwordx4 v[228:231], v[26:27], off
	global_load_dwordx4 v[232:235], v[26:27], off offset:16
	global_load_dwordx4 v[236:239], v[26:27], off offset:32
	global_load_dwordx4 v[240:243], v[26:27], off offset:48
	s_waitcnt vmcnt(0) lgkmcnt(1)
	v_add_f32_e32 v16, v20, v16
	v_add_f32_e32 v17, v21, v17
	v_add_f32_e32 v20, v22, v18
	v_add_f32_e32 v21, v23, v19
	s_waitcnt lgkmcnt(0)
	v_add_f32_e32 v22, v12, v8
	v_add_f32_e32 v23, v13, v9
	v_add_f32_e32 v25, v14, v10
	v_add_f32_e32 v36, v15, v11
	v_mov_b32_e32 v8, v228
	v_mov_b32_e32 v9, v229
	v_mov_b32_e32 v10, v230
	v_mov_b32_e32 v11, v231
	v_mov_b32_e32 v15, v5
	v_cndmask_b32_e64 v14, v16, -v16, s[0:1]
	v_cndmask_b32_e64 v20, v20, -v20, s[0:1]
	v_cndmask_b32_e64 v22, v22, -v22, s[0:1]
	s_waitcnt vmcnt(0) lgkmcnt(0)
	v_mov_b32_e32 v12, v9
	v_cndmask_b32_e64 v9, v17, -v17, s[0:1]
	v_mov_b32_e32 v5, v9
	v_mov_b32_e32 v9, v11
	v_mov_b32_e32 v13, v10
	v_pk_mul_f32 v[16:17], v[4:5], v[8:9]
	v_mov_b32_e32 v8, v232
	v_mov_b32_e32 v9, v233
	v_mov_b32_e32 v10, v234
	v_mov_b32_e32 v11, v235
	v_cndmask_b32_e64 v4, v21, -v21, s[0:1]
	v_mov_b32_e32 v21, v7
	v_mov_b32_e32 v7, v4
	s_waitcnt vmcnt(0) lgkmcnt(0)
	v_mov_b32_e32 v18, v9
	v_mov_b32_e32 v9, v11
	v_pk_mul_f32 v[8:9], v[6:7], v[8:9]
	v_mov_b32_e32 v4, v236
	v_mov_b32_e32 v5, v237
	v_mov_b32_e32 v6, v238
	v_mov_b32_e32 v7, v239
	v_mov_b32_e32 v19, v10
	s_waitcnt vmcnt(0) lgkmcnt(0)
	v_mov_b32_e32 v10, v5
	v_cndmask_b32_e64 v5, v23, -v23, s[0:1]
	v_mov_b32_e32 v23, v1
	v_mov_b32_e32 v1, v5
	v_mov_b32_e32 v5, v7
	v_mov_b32_e32 v11, v6
	v_pk_mul_f32 v[0:1], v[0:1], v[4:5]
	v_mov_b32_e32 v4, v240
	v_mov_b32_e32 v5, v241
	v_mov_b32_e32 v6, v242
	v_mov_b32_e32 v7, v243
	v_pk_fma_f32 v[0:1], v[22:23], v[10:11], v[0:1]
	s_waitcnt vmcnt(0) lgkmcnt(0)
	v_mul_f32_e32 v2, v2, v4
	v_cndmask_b32_e64 v4, v25, -v25, s[0:1]
	v_mul_f32_e32 v26, v4, v5
	v_cndmask_b32_e64 v5, v36, -v36, s[0:1]
	v_mov_b32_e32 v4, v3
	v_pk_mul_f32 v[4:5], v[4:5], v[6:7]
	v_pk_fma_f32 v[6:7], v[20:21], v[18:19], v[8:9]
	v_mov_b32_e32 v3, v4
	v_mov_b32_e32 v27, v5
	v_pk_fma_f32 v[4:5], v[14:15], v[12:13], v[16:17]
	v_pk_add_f32 v[2:3], v[2:3], v[26:27]

; DI unsigned pk2(float a, float b) { hwf32x2 f = {a, b}; hwbf16x2 r = __builtin_convertvector(f, hwbf16x2); return __builtin_bit_cast(unsigned, r); }
;   DI void operator()(int mt, int nt, int wm, int wn, int r, int h, f32x16 (&acc)[WM][2]) const {
;     ...
;       if (nt == 4 || nt == 5 || nt == 17) {
; #pragma unroll
;         for (int j = 0; j < 8; ++j) {
;           const int id = tid + 256 * j;
;           const int c = id & 127, rg = id >> 7;
;           const int lr0 = rg * 8;
;           const int row = mt * (WM * 64) + (lr0 >> 6) * (WM * 32) + ps * 64 + (lr0 & 63);
;           const int b = row / NTOK, t = row % NTOK;
;           const int col = nt * 128 + c;
;           const float bb = bias[col];
;           float x[8];
; #pragma unroll
;           for (int k = 0; k < 8; ++k) x[k] = T[(lr0 + k) * LD + c] + bb;
;           bf16_t* vt = (nt == 17) ? VTC + ((size_t)b * 128 + (col - C_V)) * NTOK : VTA + ((size_t)b * 256 + (col - A_V)) * NTOK;
;           *(uint4*)(vt + t) = make_uint4(pk2(x[0], x[1]), pk2(x[2], x[3]), pk2(x[4], x[5]), pk2(x[6], x[7]));
.LBB0_357:
	s_andn2_b64 vcc, exec, s[0:1]
	s_cbranch_vccnz .LBB0_162
	global_load_dword v244, v[68:69], off
	v_and_or_b32 v3, v94, 56, v28
	v_mul_hi_i32 v0, v3, s55
	v_lshrrev_b32_e32 v1, 31, v0
	v_ashrrev_i32_e32 v0, 9, v0
	v_mad_u64_u32 v[4:5], s[0:1], v85, s66, v[66:67]
	v_add_u32_e32 v0, v0, v1
	v_add_u32_e32 v1, 0x400, v4
	ds_read2_b32 v[8:9], v1 offset0:8 offset1:140
	v_add_u32_e32 v1, 0x800, v4
	v_mad_u64_u32 v[12:13], s[0:1], v84, s66, v[66:67]
	ds_read2_b32 v[6:7], v4 offset1:132
	ds_read2_b32 v[10:11], v1 offset0:16 offset1:148
	ds_read_b32 v4, v4 offset:3168
	ds_read_b32 v5, v12
	v_cndmask_b32_e64 v12, 0, 1, s[20:21]
	v_ashrrev_i32_e32 v1, 31, v0
	s_mov_b64 s[4:5], -1
	v_cmp_ne_u32_e64 s[0:1], 1, v12
	s_andn2_b64 vcc, exec, s[20:21]
	s_cbranch_vccnz .LBB0_360
	v_lshlrev_b64 v[12:13], 8, v[0:1]
	v_lshl_add_u64 v[12:13], v[12:13], 0, v[64:65]
	s_mov_b64 s[4:5], 0

; DI unsigned pk2(float a, float b) { hwf32x2 f = {a, b}; hwbf16x2 r = __builtin_convertvector(f, hwbf16x2); return __builtin_bit_cast(unsigned, r); }
;   DI void operator()(int mt, int nt, int wm, int wn, int r, int h, f32x16 (&acc)[WM][2]) const {
;     ...
;         for (int j = 0; j < 8; ++j) {
;           const int id = tid + 256 * j;
;           const int c = id & 127, rg = id >> 7;
;           const int lr0 = rg * 8;
;           const int row = mt * (WM * 64) + (lr0 >> 6) * (WM * 32) + ps * 64 + (lr0 & 63);
;           const int b = row / NTOK, t = row % NTOK;
;           const int col = nt * 128 + c;
;           const float bb = bias[col];
;           float x[8];
; #pragma unroll
;           for (int k = 0; k < 8; ++k) x[k] = T[(lr0 + k) * LD + c] + bb;
;           bf16_t* vt = (nt == 17) ? VTC + ((size_t)b * 128 + (col - C_V)) * NTOK : VTA + ((size_t)b * 256 + (col - A_V)) * NTOK;
;           *(uint4*)(vt + t) = make_uint4(pk2(x[0], x[1]), pk2(x[2], x[3]), pk2(x[4], x[5]), pk2(x[6], x[7]));
.LBB0_362:
	s_add_u32 s4, s68, s4
	v_mul_i32_i24_e32 v0, 0x900, v0
	s_addc_u32 s5, s69, s5
	v_sub_u32_e32 v14, v3, v0
	v_mov_b64_e32 v[0:1], s[4:5]
	v_mad_u64_u32 v[16:17], s[4:5], v12, s67, v[0:1]
	v_mov_b32_e32 v0, v17
	v_mad_u64_u32 v[0:1], s[4:5], v13, s67, v[0:1]
	s_waitcnt vmcnt(0) lgkmcnt(0)
	v_mov_b32_e32 v2, v244
	v_pk_add_f32 v[6:7], v[2:3], v[6:7] op_sel_hi:[0,1]
	v_pk_add_f32 v[8:9], v[2:3], v[8:9] op_sel_hi:[0,1]
	v_pk_add_f32 v[10:11], v[2:3], v[10:11] op_sel_hi:[0,1]
	v_pk_add_f32 v[4:5], v[2:3], v[4:5] op_sel_hi:[0,1]
	v_mov_b32_e32 v17, v0
	v_ashrrev_i32_e32 v15, 31, v14
	v_cvt_pk_bf16_f32 v0, v6, v7
	v_cvt_pk_bf16_f32 v1, v8, v9
	v_cvt_pk_bf16_f32 v2, v10, v11
	v_cvt_pk_bf16_f32 v3, v4, v5
	v_lshl_add_u64 v[4:5], v[14:15], 1, v[16:17]
	global_store_dwordx4 v[4:5], v[0:3], off
	s_nop 0
	s_and_b64 vcc, exec, s[0:1]
	v_and_b32_e32 v2, 0xffffff8, v95
	v_and_or_b32 v1, v95, 56, v29
	v_mad_u64_u32 v[8:9], s[4:5], v2, s66, v[66:67]
	v_mul_hi_i32 v3, v1, s55
	v_add_u32_e32 v4, 0x400, v8
	v_add_u32_e32 v6, 0x800, v8
	v_or_b32_e32 v9, 7, v95
	v_lshrrev_b32_e32 v12, 31, v3
	v_ashrrev_i32_e32 v13, 9, v3
	ds_read2_b32 v[2:3], v8 offset1:132
	ds_read2_b32 v[4:5], v4 offset0:8 offset1:140
	ds_read2_b32 v[6:7], v6 offset0:16 offset1:148
	v_mad_u64_u32 v[10:11], s[4:5], v9, s66, v[66:67]
	ds_read_b32 v8, v8 offset:3168
	ds_read_b32 v9, v10
	v_add_u32_e32 v12, v13, v12
	v_ashrrev_i32_e32 v13, 31, v12
	s_mov_b64 s[4:5], -1
	s_cbranch_vccnz .LBB0_364
	v_lshlrev_b64 v[10:11], 8, v[12:13]
	v_lshl_add_u64 v[10:11], v[10:11], 0, v[64:65]
	s_mov_b64 s[4:5], 0

; DI unsigned pk2(float a, float b) { hwf32x2 f = {a, b}; hwbf16x2 r = __builtin_convertvector(f, hwbf16x2); return __builtin_bit_cast(unsigned, r); }
;   DI void operator()(int mt, int nt, int wm, int wn, int r, int h, f32x16 (&acc)[WM][2]) const {
;     ...
;         for (int j = 0; j < 8; ++j) {
;           const int id = tid + 256 * j;
;           const int c = id & 127, rg = id >> 7;
;           const int lr0 = rg * 8;
;           const int row = mt * (WM * 64) + (lr0 >> 6) * (WM * 32) + ps * 64 + (lr0 & 63);
;           const int b = row / NTOK, t = row % NTOK;
;           const int col = nt * 128 + c;
;           const float bb = bias[col];
;           float x[8];
; #pragma unroll
;           for (int k = 0; k < 8; ++k) x[k] = T[(lr0 + k) * LD + c] + bb;
;           bf16_t* vt = (nt == 17) ? VTC + ((size_t)b * 128 + (col - C_V)) * NTOK : VTA + ((size_t)b * 256 + (col - A_V)) * NTOK;
;           *(uint4*)(vt + t) = make_uint4(pk2(x[0], x[1]), pk2(x[2], x[3]), pk2(x[4], x[5]), pk2(x[6], x[7]));
.LBB0_366:
	s_add_u32 s4, s68, s4
	s_waitcnt lgkmcnt(0)
	v_mov_b32_e32 v0, v244
	v_pk_add_f32 v[2:3], v[0:1], v[2:3] op_sel_hi:[0,1]
	v_pk_add_f32 v[4:5], v[0:1], v[4:5] op_sel_hi:[0,1]
	v_pk_add_f32 v[6:7], v[0:1], v[6:7] op_sel_hi:[0,1]
	v_pk_add_f32 v[8:9], v[0:1], v[8:9] op_sel_hi:[0,1]
	v_mul_i32_i24_e32 v0, 0x900, v12
	s_addc_u32 s5, s69, s5
	v_sub_u32_e32 v12, v1, v0
	v_mov_b64_e32 v[0:1], s[4:5]
	v_mad_u64_u32 v[14:15], s[4:5], v10, s67, v[0:1]
	v_mov_b32_e32 v0, v15
	v_mad_u64_u32 v[0:1], s[4:5], v11, s67, v[0:1]
	v_mov_b32_e32 v15, v0
	v_ashrrev_i32_e32 v13, 31, v12
	v_cvt_pk_bf16_f32 v0, v2, v3
	v_cvt_pk_bf16_f32 v1, v4, v5
	v_cvt_pk_bf16_f32 v2, v6, v7
	v_cvt_pk_bf16_f32 v3, v8, v9
	v_lshl_add_u64 v[4:5], v[12:13], 1, v[14:15]
	global_store_dwordx4 v[4:5], v[0:3], off
	s_nop 0
	s_and_b64 vcc, exec, s[0:1]
	v_and_b32_e32 v2, 0xffffff8, v96
	v_and_or_b32 v1, v96, 56, v30
	v_mad_u64_u32 v[8:9], s[4:5], v2, s66, v[66:67]
	v_mul_hi_i32 v3, v1, s55
	v_add_u32_e32 v4, 0x400, v8
	v_add_u32_e32 v6, 0x800, v8
	v_or_b32_e32 v9, 7, v96
	v_lshrrev_b32_e32 v12, 31, v3
	v_ashrrev_i32_e32 v13, 9, v3
	ds_read2_b32 v[2:3], v8 offset1:132
	ds_read2_b32 v[4:5], v4 offset0:8 offset1:140
	ds_read2_b32 v[6:7], v6 offset0:16 offset1:148
	v_mad_u64_u32 v[10:11], s[4:5], v9, s66, v[66:67]
	ds_read_b32 v8, v8 offset:3168
	ds_read_b32 v9, v10
	v_add_u32_e32 v12, v13, v12
	v_ashrrev_i32_e32 v13, 31, v12
	s_mov_b64 s[4:5], -1
	s_cbranch_vccnz .LBB0_368
	v_lshlrev_b64 v[10:11], 8, v[12:13]
	v_lshl_add_u64 v[10:11], v[10:11], 0, v[64:65]
	s_mov_b64 s[4:5], 0

; DI unsigned pk2(float a, float b) { hwf32x2 f = {a, b}; hwbf16x2 r = __builtin_convertvector(f, hwbf16x2); return __builtin_bit_cast(unsigned, r); }
;   DI void operator()(int mt, int nt, int wm, int wn, int r, int h, f32x16 (&acc)[WM][2]) const {
;     ...
;         for (int j = 0; j < 8; ++j) {
;           const int id = tid + 256 * j;
;           const int c = id & 127, rg = id >> 7;
;           const int lr0 = rg * 8;
;           const int row = mt * (WM * 64) + (lr0 >> 6) * (WM * 32) + ps * 64 + (lr0 & 63);
;           const int b = row / NTOK, t = row % NTOK;
;           const int col = nt * 128 + c;
;           const float bb = bias[col];
;           float x[8];
; #pragma unroll
;           for (int k = 0; k < 8; ++k) x[k] = T[(lr0 + k) * LD + c] + bb;
;           bf16_t* vt = (nt == 17) ? VTC + ((size_t)b * 128 + (col - C_V)) * NTOK : VTA + ((size_t)b * 256 + (col - A_V)) * NTOK;
;           *(uint4*)(vt + t) = make_uint4(pk2(x[0], x[1]), pk2(x[2], x[3]), pk2(x[4], x[5]), pk2(x[6], x[7]));
.LBB0_370:
	s_add_u32 s4, s68, s4
	s_waitcnt lgkmcnt(0)
	v_mov_b32_e32 v0, v244
	v_pk_add_f32 v[2:3], v[0:1], v[2:3] op_sel_hi:[0,1]
	v_pk_add_f32 v[4:5], v[0:1], v[4:5] op_sel_hi:[0,1]
	v_pk_add_f32 v[6:7], v[0:1], v[6:7] op_sel_hi:[0,1]
	v_pk_add_f32 v[8:9], v[0:1], v[8:9] op_sel_hi:[0,1]
	v_mul_i32_i24_e32 v0, 0x900, v12
	s_addc_u32 s5, s69, s5
	v_sub_u32_e32 v12, v1, v0
	v_mov_b64_e32 v[0:1], s[4:5]
	v_mad_u64_u32 v[14:15], s[4:5], v10, s67, v[0:1]
	v_mov_b32_e32 v0, v15
	v_mad_u64_u32 v[0:1], s[4:5], v11, s67, v[0:1]
	v_mov_b32_e32 v15, v0
	v_ashrrev_i32_e32 v13, 31, v12
	v_cvt_pk_bf16_f32 v0, v2, v3
	v_cvt_pk_bf16_f32 v1, v4, v5
	v_cvt_pk_bf16_f32 v2, v6, v7
	v_cvt_pk_bf16_f32 v3, v8, v9
	v_lshl_add_u64 v[4:5], v[12:13], 1, v[14:15]
	global_store_dwordx4 v[4:5], v[0:3], off
	s_nop 0
	s_and_b64 vcc, exec, s[0:1]
	v_and_b32_e32 v2, 0xffffff8, v97
	v_and_or_b32 v1, v97, 56, v31
	v_mad_u64_u32 v[8:9], s[4:5], v2, s66, v[66:67]
	v_mul_hi_i32 v3, v1, s55
	v_add_u32_e32 v4, 0x400, v8
	v_add_u32_e32 v6, 0x800, v8
	v_or_b32_e32 v9, 7, v97
	v_lshrrev_b32_e32 v12, 31, v3
	v_ashrrev_i32_e32 v13, 9, v3
	ds_read2_b32 v[2:3], v8 offset1:132
	ds_read2_b32 v[4:5], v4 offset0:8 offset1:140
	ds_read2_b32 v[6:7], v6 offset0:16 offset1:148
	v_mad_u64_u32 v[10:11], s[4:5], v9, s66, v[66:67]
	ds_read_b32 v8, v8 offset:3168
	ds_read_b32 v9, v10
	v_add_u32_e32 v12, v13, v12
	v_ashrrev_i32_e32 v13, 31, v12
	s_mov_b64 s[4:5], -1
	s_cbranch_vccnz .LBB0_372
	v_lshlrev_b64 v[10:11], 8, v[12:13]
	v_lshl_add_u64 v[10:11], v[10:11], 0, v[64:65]
	s_mov_b64 s[4:5], 0

; DI unsigned pk2(float a, float b) { hwf32x2 f = {a, b}; hwbf16x2 r = __builtin_convertvector(f, hwbf16x2); return __builtin_bit_cast(unsigned, r); }
;   DI void operator()(int mt, int nt, int wm, int wn, int r, int h, f32x16 (&acc)[WM][2]) const {
;     ...
;         for (int j = 0; j < 8; ++j) {
;           const int id = tid + 256 * j;
;           const int c = id & 127, rg = id >> 7;
;           const int lr0 = rg * 8;
;           const int row = mt * (WM * 64) + (lr0 >> 6) * (WM * 32) + ps * 64 + (lr0 & 63);
;           const int b = row / NTOK, t = row % NTOK;
;           const int col = nt * 128 + c;
;           const float bb = bias[col];
;           float x[8];
; #pragma unroll
;           for (int k = 0; k < 8; ++k) x[k] = T[(lr0 + k) * LD + c] + bb;
;           bf16_t* vt = (nt == 17) ? VTC + ((size_t)b * 128 + (col - C_V)) * NTOK : VTA + ((size_t)b * 256 + (col - A_V)) * NTOK;
;           *(uint4*)(vt + t) = make_uint4(pk2(x[0], x[1]), pk2(x[2], x[3]), pk2(x[4], x[5]), pk2(x[6], x[7]));
.LBB0_374:
	s_add_u32 s4, s68, s4
	s_waitcnt lgkmcnt(0)
	v_mov_b32_e32 v0, v244
	v_pk_add_f32 v[2:3], v[0:1], v[2:3] op_sel_hi:[0,1]
	v_pk_add_f32 v[4:5], v[0:1], v[4:5] op_sel_hi:[0,1]
	v_pk_add_f32 v[6:7], v[0:1], v[6:7] op_sel_hi:[0,1]
	v_pk_add_f32 v[8:9], v[0:1], v[8:9] op_sel_hi:[0,1]
	v_mul_i32_i24_e32 v0, 0x900, v12
	s_addc_u32 s5, s69, s5
	v_sub_u32_e32 v12, v1, v0
	v_mov_b64_e32 v[0:1], s[4:5]
	v_mad_u64_u32 v[14:15], s[4:5], v10, s67, v[0:1]
	v_mov_b32_e32 v0, v15
	v_mad_u64_u32 v[0:1], s[4:5], v11, s67, v[0:1]
	v_mov_b32_e32 v15, v0
	v_ashrrev_i32_e32 v13, 31, v12
	v_cvt_pk_bf16_f32 v0, v2, v3
	v_cvt_pk_bf16_f32 v1, v4, v5
	v_cvt_pk_bf16_f32 v2, v6, v7
	v_cvt_pk_bf16_f32 v3, v8, v9
	v_lshl_add_u64 v[4:5], v[12:13], 1, v[14:15]
	global_store_dwordx4 v[4:5], v[0:3], off
	s_nop 0
	s_and_b64 vcc, exec, s[0:1]
	v_and_b32_e32 v2, 0xffffff8, v98
	v_and_or_b32 v1, v98, 56, v32
	v_mad_u64_u32 v[8:9], s[4:5], v2, s66, v[66:67]
	v_mul_hi_i32 v3, v1, s55
	v_add_u32_e32 v4, 0x400, v8
	v_add_u32_e32 v6, 0x800, v8
	v_or_b32_e32 v9, 7, v98
	v_lshrrev_b32_e32 v12, 31, v3
	v_ashrrev_i32_e32 v13, 9, v3
	ds_read2_b32 v[2:3], v8 offset1:132
	ds_read2_b32 v[4:5], v4 offset0:8 offset1:140
	ds_read2_b32 v[6:7], v6 offset0:16 offset1:148
	v_mad_u64_u32 v[10:11], s[4:5], v9, s66, v[66:67]
	ds_read_b32 v8, v8 offset:3168
	ds_read_b32 v9, v10
	v_add_u32_e32 v12, v13, v12
	v_ashrrev_i32_e32 v13, 31, v12
	s_mov_b64 s[4:5], -1
	s_cbranch_vccnz .LBB0_376
	v_lshlrev_b64 v[10:11], 8, v[12:13]
	v_lshl_add_u64 v[10:11], v[10:11], 0, v[64:65]
	s_mov_b64 s[4:5], 0

; DI unsigned pk2(float a, float b) { hwf32x2 f = {a, b}; hwbf16x2 r = __builtin_convertvector(f, hwbf16x2); return __builtin_bit_cast(unsigned, r); }
;   DI void operator()(int mt, int nt, int wm, int wn, int r, int h, f32x16 (&acc)[WM][2]) const {
;     ...
;         for (int j = 0; j < 8; ++j) {
;           const int id = tid + 256 * j;
;           const int c = id & 127, rg = id >> 7;
;           const int lr0 = rg * 8;
;           const int row = mt * (WM * 64) + (lr0 >> 6) * (WM * 32) + ps * 64 + (lr0 & 63);
;           const int b = row / NTOK, t = row % NTOK;
;           const int col = nt * 128 + c;
;           const float bb = bias[col];
;           float x[8];
; #pragma unroll
;           for (int k = 0; k < 8; ++k) x[k] = T[(lr0 + k) * LD + c] + bb;
;           bf16_t* vt = (nt == 17) ? VTC + ((size_t)b * 128 + (col - C_V)) * NTOK : VTA + ((size_t)b * 256 + (col - A_V)) * NTOK;
;           *(uint4*)(vt + t) = make_uint4(pk2(x[0], x[1]), pk2(x[2], x[3]), pk2(x[4], x[5]), pk2(x[6], x[7]));
.LBB0_378:
	s_add_u32 s4, s68, s4
	s_waitcnt lgkmcnt(0)
	v_mov_b32_e32 v0, v244
	v_pk_add_f32 v[2:3], v[0:1], v[2:3] op_sel_hi:[0,1]
	v_pk_add_f32 v[4:5], v[0:1], v[4:5] op_sel_hi:[0,1]
	v_pk_add_f32 v[6:7], v[0:1], v[6:7] op_sel_hi:[0,1]
	v_pk_add_f32 v[8:9], v[0:1], v[8:9] op_sel_hi:[0,1]
	v_mul_i32_i24_e32 v0, 0x900, v12
	s_addc_u32 s5, s69, s5
	v_sub_u32_e32 v12, v1, v0
	v_mov_b64_e32 v[0:1], s[4:5]
	v_mad_u64_u32 v[14:15], s[4:5], v10, s67, v[0:1]
	v_mov_b32_e32 v0, v15
	v_mad_u64_u32 v[0:1], s[4:5], v11, s67, v[0:1]
	v_mov_b32_e32 v15, v0
	v_ashrrev_i32_e32 v13, 31, v12
	v_cvt_pk_bf16_f32 v0, v2, v3
	v_cvt_pk_bf16_f32 v1, v4, v5
	v_cvt_pk_bf16_f32 v2, v6, v7
	v_cvt_pk_bf16_f32 v3, v8, v9
	v_lshl_add_u64 v[4:5], v[12:13], 1, v[14:15]
	global_store_dwordx4 v[4:5], v[0:3], off
	s_nop 0
	s_and_b64 vcc, exec, s[0:1]
	v_and_b32_e32 v2, 0xffffff8, v99
	v_and_or_b32 v1, v99, 56, v33
	v_mad_u64_u32 v[8:9], s[4:5], v2, s66, v[66:67]
	v_mul_hi_i32 v3, v1, s55
	v_add_u32_e32 v4, 0x400, v8
	v_add_u32_e32 v6, 0x800, v8
	v_or_b32_e32 v9, 7, v99
	v_lshrrev_b32_e32 v12, 31, v3
	v_ashrrev_i32_e32 v13, 9, v3
	ds_read2_b32 v[2:3], v8 offset1:132
	ds_read2_b32 v[4:5], v4 offset0:8 offset1:140
	ds_read2_b32 v[6:7], v6 offset0:16 offset1:148
	v_mad_u64_u32 v[10:11], s[4:5], v9, s66, v[66:67]
	ds_read_b32 v8, v8 offset:3168
	ds_read_b32 v9, v10
	v_add_u32_e32 v12, v13, v12
	v_ashrrev_i32_e32 v13, 31, v12
	s_mov_b64 s[4:5], -1
	s_cbranch_vccnz .LBB0_380
	v_lshlrev_b64 v[10:11], 8, v[12:13]
	v_lshl_add_u64 v[10:11], v[10:11], 0, v[64:65]
	s_mov_b64 s[4:5], 0

; DI unsigned pk2(float a, float b) { hwf32x2 f = {a, b}; hwbf16x2 r = __builtin_convertvector(f, hwbf16x2); return __builtin_bit_cast(unsigned, r); }
;   DI void operator()(int mt, int nt, int wm, int wn, int r, int h, f32x16 (&acc)[WM][2]) const {
;     ...
;         for (int j = 0; j < 8; ++j) {
;           const int id = tid + 256 * j;
;           const int c = id & 127, rg = id >> 7;
;           const int lr0 = rg * 8;
;           const int row = mt * (WM * 64) + (lr0 >> 6) * (WM * 32) + ps * 64 + (lr0 & 63);
;           const int b = row / NTOK, t = row % NTOK;
;           const int col = nt * 128 + c;
;           const float bb = bias[col];
;           float x[8];
; #pragma unroll
;           for (int k = 0; k < 8; ++k) x[k] = T[(lr0 + k) * LD + c] + bb;
;           bf16_t* vt = (nt == 17) ? VTC + ((size_t)b * 128 + (col - C_V)) * NTOK : VTA + ((size_t)b * 256 + (col - A_V)) * NTOK;
;           *(uint4*)(vt + t) = make_uint4(pk2(x[0], x[1]), pk2(x[2], x[3]), pk2(x[4], x[5]), pk2(x[6], x[7]));
.LBB0_382:
	s_add_u32 s4, s68, s4
	s_waitcnt lgkmcnt(0)
	v_mov_b32_e32 v0, v244
	v_pk_add_f32 v[2:3], v[0:1], v[2:3] op_sel_hi:[0,1]
	v_pk_add_f32 v[4:5], v[0:1], v[4:5] op_sel_hi:[0,1]
	v_pk_add_f32 v[6:7], v[0:1], v[6:7] op_sel_hi:[0,1]
	v_pk_add_f32 v[8:9], v[0:1], v[8:9] op_sel_hi:[0,1]
	v_mul_i32_i24_e32 v0, 0x900, v12
	s_addc_u32 s5, s69, s5
	v_sub_u32_e32 v12, v1, v0
	v_mov_b64_e32 v[0:1], s[4:5]
	v_mad_u64_u32 v[14:15], s[4:5], v10, s67, v[0:1]
	v_mov_b32_e32 v0, v15
	v_mad_u64_u32 v[0:1], s[4:5], v11, s67, v[0:1]
	v_mov_b32_e32 v15, v0
	v_ashrrev_i32_e32 v13, 31, v12
	v_cvt_pk_bf16_f32 v0, v2, v3
	v_cvt_pk_bf16_f32 v1, v4, v5
	v_cvt_pk_bf16_f32 v2, v6, v7
	v_cvt_pk_bf16_f32 v3, v8, v9
	v_lshl_add_u64 v[4:5], v[12:13], 1, v[14:15]
	global_store_dwordx4 v[4:5], v[0:3], off
	s_nop 0
	s_and_b64 vcc, exec, s[0:1]
	v_and_b32_e32 v2, 0xffffff8, v100
	v_and_or_b32 v1, v100, 56, v34
	v_mad_u64_u32 v[8:9], s[4:5], v2, s66, v[66:67]
	v_mul_hi_i32 v3, v1, s55
	v_add_u32_e32 v4, 0x400, v8
	v_add_u32_e32 v6, 0x800, v8
	v_or_b32_e32 v9, 7, v100
	v_lshrrev_b32_e32 v12, 31, v3
	v_ashrrev_i32_e32 v13, 9, v3
	ds_read2_b32 v[2:3], v8 offset1:132
	ds_read2_b32 v[4:5], v4 offset0:8 offset1:140
	ds_read2_b32 v[6:7], v6 offset0:16 offset1:148
	v_mad_u64_u32 v[10:11], s[4:5], v9, s66, v[66:67]
	ds_read_b32 v8, v8 offset:3168
	ds_read_b32 v9, v10
	v_add_u32_e32 v12, v13, v12
	v_ashrrev_i32_e32 v13, 31, v12
	s_mov_b64 s[4:5], -1
	s_cbranch_vccnz .LBB0_384
	v_lshlrev_b64 v[10:11], 8, v[12:13]
	v_lshl_add_u64 v[10:11], v[10:11], 0, v[64:65]
	s_mov_b64 s[4:5], 0

; DI unsigned pk2(float a, float b) { hwf32x2 f = {a, b}; hwbf16x2 r = __builtin_convertvector(f, hwbf16x2); return __builtin_bit_cast(unsigned, r); }
;   DI void operator()(int mt, int nt, int wm, int wn, int r, int h, f32x16 (&acc)[WM][2]) const {
;     ...
;         for (int j = 0; j < 8; ++j) {
;           const int id = tid + 256 * j;
;           const int c = id & 127, rg = id >> 7;
;           const int lr0 = rg * 8;
;           const int row = mt * (WM * 64) + (lr0 >> 6) * (WM * 32) + ps * 64 + (lr0 & 63);
;           const int b = row / NTOK, t = row % NTOK;
;           const int col = nt * 128 + c;
;           const float bb = bias[col];
;           float x[8];
; #pragma unroll
;           for (int k = 0; k < 8; ++k) x[k] = T[(lr0 + k) * LD + c] + bb;
;           bf16_t* vt = (nt == 17) ? VTC + ((size_t)b * 128 + (col - C_V)) * NTOK : VTA + ((size_t)b * 256 + (col - A_V)) * NTOK;
;           *(uint4*)(vt + t) = make_uint4(pk2(x[0], x[1]), pk2(x[2], x[3]), pk2(x[4], x[5]), pk2(x[6], x[7]));
.LBB0_386:
	s_add_u32 s4, s68, s4
	s_waitcnt lgkmcnt(0)
	v_mov_b32_e32 v0, v244
	v_pk_add_f32 v[2:3], v[0:1], v[2:3] op_sel_hi:[0,1]
	v_pk_add_f32 v[4:5], v[0:1], v[4:5] op_sel_hi:[0,1]
	v_pk_add_f32 v[6:7], v[0:1], v[6:7] op_sel_hi:[0,1]
	v_pk_add_f32 v[8:9], v[0:1], v[8:9] op_sel_hi:[0,1]
	v_mul_i32_i24_e32 v0, 0x900, v12
	s_addc_u32 s5, s69, s5
	v_sub_u32_e32 v12, v1, v0
	v_mov_b64_e32 v[0:1], s[4:5]
	v_mad_u64_u32 v[14:15], s[4:5], v10, s67, v[0:1]
	v_mov_b32_e32 v0, v15
	v_mad_u64_u32 v[0:1], s[4:5], v11, s67, v[0:1]
	v_mov_b32_e32 v15, v0
	v_ashrrev_i32_e32 v13, 31, v12
	v_cvt_pk_bf16_f32 v0, v2, v3
	v_cvt_pk_bf16_f32 v1, v4, v5
	v_cvt_pk_bf16_f32 v2, v6, v7
	v_cvt_pk_bf16_f32 v3, v8, v9
	v_lshl_add_u64 v[4:5], v[12:13], 1, v[14:15]
	global_store_dwordx4 v[4:5], v[0:3], off
	s_nop 0
	s_and_b64 vcc, exec, s[0:1]
	v_and_b32_e32 v2, 0xffffff8, v101
	v_and_or_b32 v1, v101, 56, v35
	v_mad_u64_u32 v[8:9], s[4:5], v2, s66, v[66:67]
	v_mul_hi_i32 v3, v1, s55
	v_add_u32_e32 v4, 0x400, v8
	v_add_u32_e32 v6, 0x800, v8
	v_or_b32_e32 v9, 7, v101
	v_lshrrev_b32_e32 v12, 31, v3
	v_ashrrev_i32_e32 v13, 9, v3
	ds_read2_b32 v[2:3], v8 offset1:132
	ds_read2_b32 v[4:5], v4 offset0:8 offset1:140
	ds_read2_b32 v[6:7], v6 offset0:16 offset1:148
	v_mad_u64_u32 v[10:11], s[4:5], v9, s66, v[66:67]
	ds_read_b32 v8, v8 offset:3168
	ds_read_b32 v9, v10
	v_add_u32_e32 v12, v13, v12
	v_ashrrev_i32_e32 v13, 31, v12
	s_mov_b64 s[0:1], -1
	s_cbranch_vccnz .LBB0_388
	v_lshlrev_b64 v[10:11], 8, v[12:13]
	v_lshl_add_u64 v[10:11], v[10:11], 0, v[64:65]
	s_mov_b64 s[0:1], 0

; DI bf16_t f2bf(float f) { return (bf16_t)(pk2(f, 0.f) & 0xffffu); }
; template <int MX>
; DI void rec_output(const Params& p, int l, int b, int h, int sc, unsigned char* smem) {
;     ...
;   for (int dir = 0; dir < 2; ++dir) {
;     f32x4 St[4];
; #pragma unroll
;     for (int c = 0; c < 4; ++c) St[c] = f32x4{0.f, 0.f, 0.f, 0.f};
;     float nst = 0.f, dtot = 1.f;
;     const int npre = dir == 0 ? sc : (sc == 0 ? 0 : 1 + (8 - sc));
;     SumRegs cur = rec_ldsum<MX>(p, b, h, dir, 0, w, g, col, tid);
; #pragma unroll 1
;     for (int i = 0; i < npre; ++i) {
;       const SumRegs nxt = rec_ldsum<MX>(p, b, h, dir, (i + 1 < npre) ? i + 1 : i, w, g, col, tid);
;       St[0] = cur.d[0] * St[0] + cur.E0;
;       St[1] = cur.d[1] * St[1] + cur.E1;
;       St[2] = cur.d[2] * St[2] + cur.E2;
;       St[3] = cur.d[3] * St[3] + cur.E3;
;       if (MX == 1 && tid < 64) nst = cur.nd * nst + cur.nn;
;       cur = nxt;
;     }
;     __syncthreads();
; #pragma unroll
;     for (int c = 0; c < 4; ++c)
; #pragma unroll
;       for (int j = 0; j < 4; ++j) {
;         const int v = 16 * w + 4 * g + j, k = 16 * c + col;
;         *(bf16_t*)(smem + L_STT + swz(v, k >> 3) + (k & 7) * 2) = f2bf(St[c][j]);
;       }
;     if (MX == 1 && tid < 64) ((float*)(smem + L_N0))[tid] = nst;
;     RecRaw raw = rec_load<MX>(p, b, h, dir, sc * 256 + (dir == 0 ? 0 : 3) * 64, tid);
; #pragma unroll 1
;     for (int ci = 0; ci < 4; ++ci) {
;       const int c = dir == 0 ? ci : 3 - ci;
;       const int cn = dir == 0 ? (ci < 3 ? ci + 1 : ci) : (ci < 3 ? 2 - ci : 0);
;       const RecRaw nxt = rec_load<MX>(p, b, h, dir, sc * 256 + cn * 64, tid);
;       rec_chunk<MX, true>(p, l, b, h, dir, sc * 256 + c * 64, smem, St, nst, dtot, tid, raw);
;       raw = nxt;
;     }
;   }
.Ltr_1130:
	s_branch .LBB0_1130

; DI void ph_mixers2(const Params& p_in, int l, unsigned char* smem, volatile lds_int* slot) {
;   const int total = 512 + 576;
;   unsigned* ctr = (unsigned*)(p_in.ws + WS_CTL + 13824) + (l * 2 + 1);
;   for (;;) {
;     const int it = next_item(ctr, slot);
.LBB0_801:
	s_cmp_le_i32 s58, s28
	s_cselect_b64 s[0:1], -1, 0
	s_cmp_lt_i32 s28, s59
	s_cselect_b64 s[4:5], -1, 0
	s_and_b64 s[0:1], s[0:1], s[4:5]
	s_andn2_b64 vcc, exec, s[0:1]
	s_cbranch_vccnz .LBB0_1050
	s_lshl_b32 s2, s48, 1
	s_lshl_b64 s[0:1], s[2:3], 2
	s_add_u32 s0, s68, s0
	s_addc_u32 s1, s69, s1
	s_add_u32 s0, s0, 0xfc89604
	s_addc_u32 s1, s1, 0
	v_writelane_b32 v252, s0, 1
	s_lshl_b32 s2, s48, 6
	v_readlane_b32 s72, v253, 23
	v_writelane_b32 v252, s1, 2
	s_lshl_b32 s0, s48, 2
	v_writelane_b32 v252, s0, 3
	s_lshl_b64 s[0:1], s[2:3], 2
	v_readlane_b32 s84, v253, 35
	v_readlane_b32 s85, v253, 36
	s_add_u32 s4, s84, s0
	v_readlane_b32 s80, v253, 31
	s_addc_u32 s5, s85, s1
	v_readlane_b32 s81, v253, 32
	v_writelane_b32 v252, s4, 4
	s_add_u32 s0, s80, s0
	s_addc_u32 s1, s81, s1
	v_writelane_b32 v252, s5, 5
	v_writelane_b32 v252, s0, 6
	v_readlane_b32 s73, v253, 24
	v_readlane_b32 s74, v253, 25
	v_readlane_b32 s75, v253, 26
	v_readlane_b32 s76, v253, 27
	v_readlane_b32 s77, v253, 28
	v_readlane_b32 s78, v253, 29
	v_readlane_b32 s79, v253, 30
	v_readlane_b32 s82, v253, 33
	v_readlane_b32 s83, v253, 34
	v_readlane_b32 s86, v253, 37
	v_readlane_b32 s87, v253, 38
	v_writelane_b32 v252, s1, 7
	v_readlane_b32 s98, v253, 43
	s_nop 1
	s_cmpk_eq_i32 s98, 0x200
	s_cselect_b32 s98, 1, 0
	s_mov_b32 s99, s98
	s_branch .LBB0_805

; template <int MODE>
; DI void attn_mfma(const Params& p, int l, int b, int hd, int qb, unsigned char* smem) {
;     ...
;   const int tq = qb * QPB + (MODE ? wv : (wv & 1)) * 32 + r;
;   const size_t qrow = (size_t)b * NTOK + tq;
;   bf16x8 qf[KS];
; #pragma unroll
;   for (int ks = 0; ks < KS; ++ks) qf[ks] = *(const bf16x8*)(P + qrow * PW + qcol + (2 * (mp * 2 + ks) + h2) * 8);
;   const bool isctx = qb * QPB < NCTX;
;   int ntiles, band_lo = 0;
;   if (MODE == 0) ntiles = isctx ? 4 : 36;
;   else {
;     if (isctx) ntiles = 4;
;     else { const int i0 = qb * QPB - NCTX; int lo = i0 - 128; if (lo < 0) lo = 0; int hi = i0 + 256; if (hi > NLAT) hi = NLAT; band_lo = lo; ntiles = 4 + (hi - lo) / 64; }
;   }
;   const float cexp = (MODE ? 0.125f : 0.17677669529663687f) * 1.4426950408889634f;
;   float mrun = MODE ? p.sw_sink[l * 4 + hd] * 1.4426950408889634f : -1e30f;
;   float lsum = (MODE && h2 == 0) ? 1.f : 0.f;
;   f32x16 O[2];
; #pragma unroll
;   for (int vt = 0; vt < 2; ++vt)
; #pragma unroll
;     for (int i = 0; i < 16; ++i) O[vt][i] = 0.f;
;   const int lrow = tid >> 3, lc = tid & 7;
; DI void ph_mixers2(const Params& p_in, int l, unsigned char* smem, volatile lds_int* slot) {
;   const int total = 512 + 576;
;   unsigned* ctr = (unsigned*)(p_in.ws + WS_CTL + 13824) + (l * 2 + 1);
;   for (;;) {
;     const int it = next_item(ctr, slot);
;     if (it >= total) break;
;     Params p = p_in;
;     asm volatile("" : "+s"(p.ws));
;     if (it < 512) {
;       int r = it; const int mx = r >> 8; r &= 255;
;       const int sc = 1 + (r & 7); r >>= 3; const int h = r & 3, b = r >> 2;
;       if (mx == 0) rec_output<0>(p, l, b, h, sc, smem); else rec_output<1>(p, l, b, h, sc, smem);
;     } else { const int r = it - 512; const int qb = r % 18, bh = r / 18; if (!(l == 1 && qb < 2)) attn_mfma<1>(p, l, bh >> 2, bh & 3, qb, smem); }
.LBB0_805:
	s_waitcnt lgkmcnt(0)
	s_barrier
	s_cmp_eq_u32 s98, 1
	s_cbranch_scc0 .Lm2_dyn
	s_mov_b32 s98, 0
	v_readlane_b32 s27, v253, 42
	s_nop 1
	s_cmp_lt_u32 s27, 0x100
	s_cselect_b32 s0, 0, 0x100
	s_add_i32 s27, s27, s0
	v_mov_b32_e32 v0, s27
	s_movk_i32 s0, 0x43f
	s_branch .Lm2_have
.Lm2_dyn:
	s_and_saveexec_b64 s[0:1], s[60:61]
	s_cbranch_execz .LBB0_807
	v_readlane_b32 s4, v252, 1
	v_readlane_b32 s5, v252, 2
	s_nop 1
	v_mov_b64_e32 v[0:1], s[4:5]
	flat_atomic_add v0, v[0:1], v174 sc0
	s_waitcnt vmcnt(0) lgkmcnt(0)
	ds_write_b32 v176, v0
.LBB0_807:
	s_or_b64 exec, exec, s[0:1]
	s_waitcnt lgkmcnt(0)
	s_barrier
	ds_read_b32 v0, v176
	s_movk_i32 s0, 0x43f
	s_waitcnt lgkmcnt(0)
	s_cmp_eq_u32 s99, 1
	s_cbranch_scc0 .Lm2_have
	v_readfirstlane_b32 s27, v0
	s_nop 1
	s_cmp_lt_u32 s27, 0x100
	s_cselect_b32 s1, 1, 2
	s_lshl_b32 s1, s1, 8
	s_add_i32 s27, s27, s1
	v_mov_b32_e32 v0, s27
.Lm2_have:
	v_cmp_lt_i32_e32 vcc, s0, v0
	v_readfirstlane_b32 s27, v0
	s_mov_b64 s[0:1], -1
	s_cbranch_vccnz .LBB0_804
	s_mov_b64 s[14:15], s[68:69]
	s_cmpk_gt_i32 s27, 0x1ff
	s_cbranch_scc0 .LBB0_831
	s_add_i32 s0, s27, 0xfe00
	s_and_b32 s1, s0, 0xffff
	s_mul_i32 s1, s1, 0xe38f
	s_lshr_b32 s2, s1, 20
	s_mul_i32 s1, s2, 18
	s_sub_i32 s6, s0, s1
	s_and_b32 s0, s6, 0xffff
	s_cmp_lt_u32 s0, 2
	v_readlane_b32 s0, v254, 12
	s_cselect_b64 s[4:5], -1, 0
	v_readlane_b32 s1, v254, 13
	s_and_b64 s[0:1], s[0:1], s[4:5]
	s_and_b64 vcc, exec, s[0:1]
	s_cbranch_vccnz .LBB0_830
	s_add_u32 s0, s14, 0x41c6000
	s_addc_u32 s1, s15, 0
	s_lshl_b32 s6, s6, 7
	s_and_b32 s8, s6, 0xff80
	v_sub_u32_e64 v2, s8, v194 clamp
	s_min_u32 s6, s8, 0x800
	v_readfirstlane_b32 s9, v2
	s_sub_i32 s6, s6, s9
	s_ashr_i32 s6, s6, 6
	s_add_i32 s10, s6, 4
	s_and_b64 s[6:7], s[4:5], exec
	v_mbcnt_lo_u32_b32 v1, -1, 0
	v_mbcnt_hi_u32_b32 v1, -1, v1
	s_cselect_b32 s12, 4, s10
	v_bfe_u32 v0, v1, 5, 1
	v_cmp_eq_u32_e32 vcc, 0, v0
	s_mov_b64 s[6:7], -1
	s_cmp_gt_i32 s12, 0
	s_waitcnt vmcnt(0)
	v_lshlrev_b32_e32 v152, 2, v0
	s_cbranch_scc1 .LBB0_812
	v_mbcnt_hi_u32_b32 v32, -1, v185
	v_and_b32_e32 v2, 64, v32
	v_lshlrev_b32_e32 v35, 2, v0
	v_xor_b32_e32 v33, 32, v32
	v_add_u32_e32 v34, 64, v2
	v_or_b32_e32 v150, 8, v35
	v_or_b32_e32 v148, 16, v35
	v_or_b32_e32 v146, 24, v35
	s_mov_b64 s[6:7], 0

; __global__ void __launch_bounds__(256, 2) mk_fwd(Params p_in) {
;   __shared__ __attribute__((aligned(16))) unsigned char smem[SMEM_BYTES];
	.amdhsa_kernel _Z6mk_fwd6Params
		.amdhsa_group_segment_fixed_size 73748
		.amdhsa_private_segment_fixed_size 0
		.amdhsa_kernarg_size 424
		.amdhsa_user_sgpr_count 2
		.amdhsa_user_sgpr_dispatch_ptr 0
		.amdhsa_user_sgpr_queue_ptr 0
		.amdhsa_user_sgpr_kernarg_segment_ptr 1
		.amdhsa_user_sgpr_dispatch_id 0
		.amdhsa_user_sgpr_kernarg_preload_length 0
		.amdhsa_user_sgpr_kernarg_preload_offset 0
		.amdhsa_user_sgpr_private_segment_size 0
		.amdhsa_uses_dynamic_stack 0
		.amdhsa_enable_private_segment 0
		.amdhsa_system_sgpr_workgroup_id_x 1
		.amdhsa_system_sgpr_workgroup_id_y 0
		.amdhsa_system_sgpr_workgroup_id_z 0
		.amdhsa_system_sgpr_workgroup_info 0
		.amdhsa_system_vgpr_workitem_id 2
		.amdhsa_next_free_vgpr 255
		.amdhsa_next_free_sgpr 102
		.amdhsa_accum_offset 256
		.amdhsa_reserve_vcc 1
		.amdhsa_float_round_mode_32 0
		.amdhsa_float_round_mode_16_64 0
		.amdhsa_float_denorm_mode_32 3
		.amdhsa_float_denorm_mode_16_64 3
		.amdhsa_dx10_clamp 1
		.amdhsa_ieee_mode 1
		.amdhsa_fp16_overflow 0
		.amdhsa_tg_split 0
		.amdhsa_exception_fp_ieee_invalid_op 0
		.amdhsa_exception_fp_denorm_src 0
		.amdhsa_exception_fp_ieee_div_zero 0
		.amdhsa_exception_fp_ieee_overflow 0
		.amdhsa_exception_fp_ieee_underflow 0
		.amdhsa_exception_fp_ieee_inexact 0
		.amdhsa_exception_int_div_zero 0
	.end_amdhsa_kernel

; __global__ void __launch_bounds__(256, 2) mk_fwd(Params p_in) {
;   __shared__ __attribute__((aligned(16))) unsigned char smem[SMEM_BYTES];
amdhsa.kernels:
  - .agpr_count:     0
    .args:
      - .offset:         0
        .size:           168
        .value_kind:     by_value
      - .offset:         168
        .size:           4
        .value_kind:     hidden_block_count_x
      - .offset:         172
        .size:           4
        .value_kind:     hidden_block_count_y
      - .offset:         176
        .size:           4
        .value_kind:     hidden_block_count_z
      - .offset:         180
        .size:           2
        .value_kind:     hidden_group_size_x
      - .offset:         182
        .size:           2
        .value_kind:     hidden_group_size_y
      - .offset:         184
        .size:           2
        .value_kind:     hidden_group_size_z
      - .offset:         186
        .size:           2
        .value_kind:     hidden_remainder_x
      - .offset:         188
        .size:           2
        .value_kind:     hidden_remainder_y
      - .offset:         190
        .size:           2
        .value_kind:     hidden_remainder_z
      - .offset:         208
        .size:           8
        .value_kind:     hidden_global_offset_x
      - .offset:         216
        .size:           8
        .value_kind:     hidden_global_offset_y
      - .offset:         224
        .size:           8
        .value_kind:     hidden_global_offset_z
      - .offset:         232
        .size:           2
        .value_kind:     hidden_grid_dims
      - .offset:         256
        .size:           8
        .value_kind:     hidden_multigrid_sync_arg
    .group_segment_fixed_size: 73748
    .kernarg_segment_align: 8
    .kernarg_segment_size: 424
    .language:       OpenCL C
    .language_version:
      - 2
      - 0
    .max_flat_workgroup_size: 256
    .name:           _Z6mk_fwd6Params
    .private_segment_fixed_size: 0
    .sgpr_count:     108
    .sgpr_spill_count: 233
    .symbol:         _Z6mk_fwd6Params.kd
    .uniform_work_group_size: 1
    .uses_dynamic_stack: false
    .vgpr_count:     255
    .vgpr_spill_count: 0
    .wavefront_size: 64
